# P4 ss1 loads hoisted, gate epilogue xr loads hoisted, P1 mainloop glds saddr form
# speedup vs baseline: 1.0043x; 1.0043x over previous
.LBB0_195:
	ds_read_b128 v[128:131], v179
	ds_read_b128 v[132:135], v179 offset:1024
	ds_read_b128 v[136:139], v179 offset:2048
	ds_read_b128 v[162:165], v179 offset:3072
	ds_read_b128 v[166:169], v180
	ds_read_b128 v[170:173], v180 offset:1024
	ds_read_b128 v[194:197], v180 offset:2048
	ds_read_b128 v[198:201], v180 offset:3072
	s_add_u32 s2, s8, 0xfff80080
	s_addc_u32 s3, s9, -1
	s_cmp_eq_u32 s66, 28
	s_cselect_b32 s65, s0, s3
	s_cselect_b32 s64, s30, s2
	s_cselect_b32 s61, s31, s57
	s_cselect_b32 s60, s39, s41
	s_add_i32 m0, s72, 0xc000
	ds_read_b128 v[202:205], v181
	ds_read_b128 v[206:209], v181 offset:1024
	ds_read_b128 v[210:213], v181 offset:2048
	ds_read_b128 v[214:217], v181 offset:3072
	ds_read_b128 v[218:221], v181 offset:4096
	ds_read_b128 v[222:225], v181 offset:5120
	ds_read_b128 v[226:229], v181 offset:6144
	ds_read_b128 v[230:233], v181 offset:7168
	global_load_lds_dwordx4 v154, s[8:9]
	s_add_i32 m0, s72, 0xe000
	s_nop 0
	global_load_lds_dwordx4 v156, s[8:9]
	s_waitcnt vmcnt(8)
	s_waitcnt lgkmcnt(0)
	s_barrier
	s_setprio 1
	s_waitcnt lgkmcnt(0)
	v_mfma_f32_16x16x32_bf16 v[124:127], v[128:131], v[202:205], v[124:127]
	v_mfma_f32_16x16x32_bf16 v[120:123], v[136:139], v[202:205], v[120:123]
	v_mfma_f32_16x16x32_bf16 v[116:119], v[128:131], v[210:213], v[116:119]
	v_mfma_f32_16x16x32_bf16 v[112:115], v[136:139], v[210:213], v[112:115]
	v_mfma_f32_16x16x32_bf16 v[108:111], v[128:131], v[218:221], v[108:111]
	v_mfma_f32_16x16x32_bf16 v[104:107], v[136:139], v[218:221], v[104:107]
	v_mfma_f32_16x16x32_bf16 v[100:103], v[128:131], v[226:229], v[100:103]
	v_mfma_f32_16x16x32_bf16 v[96:99], v[136:139], v[226:229], v[96:99]
	v_mfma_f32_16x16x32_bf16 v[124:127], v[132:135], v[206:209], v[124:127]
	v_mfma_f32_16x16x32_bf16 v[120:123], v[162:165], v[206:209], v[120:123]
	v_mfma_f32_16x16x32_bf16 v[116:119], v[132:135], v[214:217], v[116:119]
	v_mfma_f32_16x16x32_bf16 v[112:115], v[162:165], v[214:217], v[112:115]
	v_mfma_f32_16x16x32_bf16 v[108:111], v[132:135], v[222:225], v[108:111]
	v_mfma_f32_16x16x32_bf16 v[104:107], v[162:165], v[222:225], v[104:107]
	v_mfma_f32_16x16x32_bf16 v[100:103], v[132:135], v[230:233], v[100:103]
	v_mfma_f32_16x16x32_bf16 v[96:99], v[162:165], v[230:233], v[96:99]
	s_setprio 0
	s_setprio 1
	v_mfma_f32_16x16x32_bf16 v[60:63], v[166:169], v[202:205], v[60:63]
	v_mfma_f32_16x16x32_bf16 v[56:59], v[194:197], v[202:205], v[56:59]
	v_mfma_f32_16x16x32_bf16 v[52:55], v[166:169], v[210:213], v[52:55]
	v_mfma_f32_16x16x32_bf16 v[48:51], v[194:197], v[210:213], v[48:51]
	v_mfma_f32_16x16x32_bf16 v[44:47], v[166:169], v[218:221], v[44:47]
	v_mfma_f32_16x16x32_bf16 v[40:43], v[194:197], v[218:221], v[40:43]
	v_mfma_f32_16x16x32_bf16 v[36:39], v[166:169], v[226:229], v[36:39]
	v_mfma_f32_16x16x32_bf16 v[32:35], v[194:197], v[226:229], v[32:35]
	v_mfma_f32_16x16x32_bf16 v[60:63], v[170:173], v[206:209], v[60:63]
	v_mfma_f32_16x16x32_bf16 v[56:59], v[198:201], v[206:209], v[56:59]
	v_mfma_f32_16x16x32_bf16 v[52:55], v[170:173], v[214:217], v[52:55]
	v_mfma_f32_16x16x32_bf16 v[48:51], v[198:201], v[214:217], v[48:51]
	v_mfma_f32_16x16x32_bf16 v[44:47], v[170:173], v[222:225], v[44:47]
	v_mfma_f32_16x16x32_bf16 v[40:43], v[198:201], v[222:225], v[40:43]
	v_mfma_f32_16x16x32_bf16 v[36:39], v[170:173], v[230:233], v[36:39]
	v_mfma_f32_16x16x32_bf16 v[32:35], v[198:201], v[230:233], v[32:35]
	s_setprio 0
	s_barrier
	s_add_i32 s2, s81, s35
	s_mov_b32 m0, s2
	ds_read_b128 v[202:205], v181 offset:16384
	ds_read_b128 v[206:209], v181 offset:17408
	ds_read_b128 v[210:213], v181 offset:18432
	ds_read_b128 v[214:217], v181 offset:19456
	ds_read_b128 v[218:221], v181 offset:20480
	ds_read_b128 v[222:225], v181 offset:21504
	ds_read_b128 v[226:229], v181 offset:22528
	ds_read_b128 v[230:233], v181 offset:23552
	global_load_lds_dwordx4 v142, s[60:61]
	s_add_i32 m0, s2, 0x2000
	s_add_u32 s2, s60, 0x80000
	s_addc_u32 s3, s61, 0
	s_add_i32 s46, s82, s35
	global_load_lds_dwordx4 v146, s[60:61]
	s_mov_b32 m0, s46
	s_nop 0
	global_load_lds_dwordx4 v142, s[2:3]
	s_add_i32 m0, s46, 0x2000
	s_nop 0
	global_load_lds_dwordx4 v146, s[2:3]
	s_mov_b32 m0, s72
	s_nop 0
	global_load_lds_dwordx4 v140, s[64:65]
	s_mov_b32 m0, s73
	s_nop 0
	global_load_lds_dwordx4 v144, s[64:65]
	s_waitcnt vmcnt(8)
	s_waitcnt lgkmcnt(0)
	s_barrier
	s_setprio 1
	s_waitcnt lgkmcnt(0)
	v_mfma_f32_16x16x32_bf16 v[92:95], v[128:131], v[202:205], v[92:95]
	v_mfma_f32_16x16x32_bf16 v[88:91], v[136:139], v[202:205], v[88:91]
	v_mfma_f32_16x16x32_bf16 v[84:87], v[128:131], v[210:213], v[84:87]
	v_mfma_f32_16x16x32_bf16 v[80:83], v[136:139], v[210:213], v[80:83]
	v_mfma_f32_16x16x32_bf16 v[76:79], v[128:131], v[218:221], v[76:79]
	v_mfma_f32_16x16x32_bf16 v[72:75], v[136:139], v[218:221], v[72:75]
	v_mfma_f32_16x16x32_bf16 v[68:71], v[128:131], v[226:229], v[68:71]
	v_mfma_f32_16x16x32_bf16 v[64:67], v[136:139], v[226:229], v[64:67]
	v_mfma_f32_16x16x32_bf16 v[92:95], v[132:135], v[206:209], v[92:95]
	v_mfma_f32_16x16x32_bf16 v[88:91], v[162:165], v[206:209], v[88:91]
	v_mfma_f32_16x16x32_bf16 v[84:87], v[132:135], v[214:217], v[84:87]
	v_mfma_f32_16x16x32_bf16 v[80:83], v[162:165], v[214:217], v[80:83]
	v_mfma_f32_16x16x32_bf16 v[76:79], v[132:135], v[222:225], v[76:79]
	v_mfma_f32_16x16x32_bf16 v[72:75], v[162:165], v[222:225], v[72:75]
	v_mfma_f32_16x16x32_bf16 v[68:71], v[132:135], v[230:233], v[68:71]
	v_mfma_f32_16x16x32_bf16 v[64:67], v[162:165], v[230:233], v[64:67]
	s_setprio 0
	s_setprio 1
	v_mfma_f32_16x16x32_bf16 v[28:31], v[166:169], v[202:205], v[28:31]
	v_mfma_f32_16x16x32_bf16 v[24:27], v[194:197], v[202:205], v[24:27]
	v_mfma_f32_16x16x32_bf16 v[20:23], v[166:169], v[210:213], v[20:23]
	v_mfma_f32_16x16x32_bf16 v[16:19], v[194:197], v[210:213], v[16:19]
	v_mfma_f32_16x16x32_bf16 v[12:15], v[166:169], v[218:221], v[12:15]
	v_mfma_f32_16x16x32_bf16 v[8:11], v[194:197], v[218:221], v[8:11]
	v_mfma_f32_16x16x32_bf16 v[4:7], v[166:169], v[226:229], v[4:7]
	v_mfma_f32_16x16x32_bf16 v[0:3], v[194:197], v[226:229], v[0:3]
	v_mfma_f32_16x16x32_bf16 v[28:31], v[170:173], v[206:209], v[28:31]
	v_mfma_f32_16x16x32_bf16 v[24:27], v[198:201], v[206:209], v[24:27]
	v_mfma_f32_16x16x32_bf16 v[20:23], v[170:173], v[214:217], v[20:23]
	v_mfma_f32_16x16x32_bf16 v[16:19], v[198:201], v[214:217], v[16:19]
	v_mfma_f32_16x16x32_bf16 v[12:15], v[170:173], v[222:225], v[12:15]
	v_mfma_f32_16x16x32_bf16 v[8:11], v[198:201], v[222:225], v[8:11]
	v_mfma_f32_16x16x32_bf16 v[4:7], v[170:173], v[230:233], v[4:7]
	v_mfma_f32_16x16x32_bf16 v[0:3], v[198:201], v[230:233], v[0:3]
	s_setprio 0
	s_barrier
	s_add_i32 s46, 0, 0x18000
	v_add_u32_e32 v148, s46, v174
	s_add_i32 s47, 0, 0x1c000
	ds_read_b128 v[128:131], v148
	ds_read_b128 v[132:135], v148 offset:1024
	ds_read_b128 v[136:139], v148 offset:2048
	ds_read_b128 v[162:165], v148 offset:3072
	v_add_u32_e32 v148, s47, v174
	ds_read_b128 v[166:169], v148
	ds_read_b128 v[170:173], v148 offset:1024
	ds_read_b128 v[194:197], v148 offset:2048
	ds_read_b128 v[198:201], v148 offset:3072
	s_add_u32 s2, s64, 0x80000
	s_addc_u32 s3, s65, 0
	s_mov_b32 m0, s74
	ds_read_b128 v[202:205], v181 offset:32768
	ds_read_b128 v[206:209], v181 offset:33792
	ds_read_b128 v[210:213], v181 offset:34816
	ds_read_b128 v[214:217], v181 offset:35840
	ds_read_b128 v[218:221], v181 offset:36864
	ds_read_b128 v[222:225], v181 offset:37888
	ds_read_b128 v[226:229], v181 offset:38912
	ds_read_b128 v[230:233], v181 offset:39936
	global_load_lds_dwordx4 v140, s[2:3]
	s_mov_b32 m0, s75
	s_nop 0
	global_load_lds_dwordx4 v144, s[2:3]
	s_waitcnt vmcnt(8)
	s_waitcnt lgkmcnt(0)
	s_barrier
	s_setprio 1
	s_waitcnt lgkmcnt(0)
	v_mfma_f32_16x16x32_bf16 v[124:127], v[128:131], v[202:205], v[124:127]
	v_mfma_f32_16x16x32_bf16 v[120:123], v[136:139], v[202:205], v[120:123]
	v_mfma_f32_16x16x32_bf16 v[116:119], v[128:131], v[210:213], v[116:119]
	v_mfma_f32_16x16x32_bf16 v[112:115], v[136:139], v[210:213], v[112:115]
	v_mfma_f32_16x16x32_bf16 v[108:111], v[128:131], v[218:221], v[108:111]
	v_mfma_f32_16x16x32_bf16 v[104:107], v[136:139], v[218:221], v[104:107]
	v_mfma_f32_16x16x32_bf16 v[100:103], v[128:131], v[226:229], v[100:103]
	v_mfma_f32_16x16x32_bf16 v[96:99], v[136:139], v[226:229], v[96:99]
	v_mfma_f32_16x16x32_bf16 v[124:127], v[132:135], v[206:209], v[124:127]
	v_mfma_f32_16x16x32_bf16 v[120:123], v[162:165], v[206:209], v[120:123]
	v_mfma_f32_16x16x32_bf16 v[116:119], v[132:135], v[214:217], v[116:119]
	v_mfma_f32_16x16x32_bf16 v[112:115], v[162:165], v[214:217], v[112:115]
	v_mfma_f32_16x16x32_bf16 v[108:111], v[132:135], v[222:225], v[108:111]
	v_mfma_f32_16x16x32_bf16 v[104:107], v[162:165], v[222:225], v[104:107]
	v_mfma_f32_16x16x32_bf16 v[100:103], v[132:135], v[230:233], v[100:103]
	v_mfma_f32_16x16x32_bf16 v[96:99], v[162:165], v[230:233], v[96:99]
	s_setprio 0
	s_setprio 1
	v_mfma_f32_16x16x32_bf16 v[60:63], v[166:169], v[202:205], v[60:63]
	v_mfma_f32_16x16x32_bf16 v[56:59], v[194:197], v[202:205], v[56:59]
	v_mfma_f32_16x16x32_bf16 v[52:55], v[166:169], v[210:213], v[52:55]
	v_mfma_f32_16x16x32_bf16 v[48:51], v[194:197], v[210:213], v[48:51]
	v_mfma_f32_16x16x32_bf16 v[44:47], v[166:169], v[218:221], v[44:47]
	v_mfma_f32_16x16x32_bf16 v[40:43], v[194:197], v[218:221], v[40:43]
	v_mfma_f32_16x16x32_bf16 v[36:39], v[166:169], v[226:229], v[36:39]
	v_mfma_f32_16x16x32_bf16 v[32:35], v[194:197], v[226:229], v[32:35]
	v_mfma_f32_16x16x32_bf16 v[60:63], v[170:173], v[206:209], v[60:63]
	v_mfma_f32_16x16x32_bf16 v[56:59], v[198:201], v[206:209], v[56:59]
	v_mfma_f32_16x16x32_bf16 v[52:55], v[170:173], v[214:217], v[52:55]
	v_mfma_f32_16x16x32_bf16 v[48:51], v[198:201], v[214:217], v[48:51]
	v_mfma_f32_16x16x32_bf16 v[44:47], v[170:173], v[222:225], v[44:47]
	v_mfma_f32_16x16x32_bf16 v[40:43], v[198:201], v[222:225], v[40:43]
	v_mfma_f32_16x16x32_bf16 v[36:39], v[170:173], v[230:233], v[36:39]
	v_mfma_f32_16x16x32_bf16 v[32:35], v[198:201], v[230:233], v[32:35]
	s_setprio 0
	s_barrier
	s_add_i32 s2, s46, s35
	s_add_i32 m0, s2, 0xffffff80
	ds_read_b128 v[202:205], v181 offset:49152
	ds_read_b128 v[206:209], v181 offset:50176
	ds_read_b128 v[210:213], v181 offset:51200
	ds_read_b128 v[214:217], v181 offset:52224
	ds_read_b128 v[218:221], v181 offset:53248
	ds_read_b128 v[222:225], v181 offset:54272
	ds_read_b128 v[226:229], v181 offset:55296
	ds_read_b128 v[230:233], v181 offset:56320
	global_load_lds_dwordx4 v142, s[60:61] offset:128
	s_add_i32 m0, s2, 0x1f80
	s_add_u32 s2, s60, 0x80080
	s_addc_u32 s3, s61, 0
	s_add_i32 s46, s47, s35
	global_load_lds_dwordx4 v146, s[60:61] offset:128
	s_mov_b32 m0, s46
	s_nop 0
	global_load_lds_dwordx4 v142, s[2:3]
	s_add_i32 m0, s46, 0x2000
	s_nop 0
	global_load_lds_dwordx4 v146, s[2:3]
	s_add_i32 m0, s76, 0xffffff80
	s_nop 0
	global_load_lds_dwordx4 v140, s[64:65] offset:128
	s_add_i32 m0, s77, 0xffffff80
	s_nop 0
	global_load_lds_dwordx4 v144, s[64:65] offset:128
	s_waitcnt vmcnt(8)
	s_waitcnt lgkmcnt(0)
	s_barrier
	s_setprio 1
	s_waitcnt lgkmcnt(0)
	v_mfma_f32_16x16x32_bf16 v[92:95], v[128:131], v[202:205], v[92:95]
	v_mfma_f32_16x16x32_bf16 v[88:91], v[136:139], v[202:205], v[88:91]
	v_mfma_f32_16x16x32_bf16 v[84:87], v[128:131], v[210:213], v[84:87]
	v_mfma_f32_16x16x32_bf16 v[80:83], v[136:139], v[210:213], v[80:83]
	v_mfma_f32_16x16x32_bf16 v[76:79], v[128:131], v[218:221], v[76:79]
	v_mfma_f32_16x16x32_bf16 v[72:75], v[136:139], v[218:221], v[72:75]
	v_mfma_f32_16x16x32_bf16 v[68:71], v[128:131], v[226:229], v[68:71]
	v_mfma_f32_16x16x32_bf16 v[64:67], v[136:139], v[226:229], v[64:67]
	v_mfma_f32_16x16x32_bf16 v[92:95], v[132:135], v[206:209], v[92:95]
	v_mfma_f32_16x16x32_bf16 v[88:91], v[162:165], v[206:209], v[88:91]
	v_mfma_f32_16x16x32_bf16 v[84:87], v[132:135], v[214:217], v[84:87]
	v_mfma_f32_16x16x32_bf16 v[80:83], v[162:165], v[214:217], v[80:83]
	v_mfma_f32_16x16x32_bf16 v[76:79], v[132:135], v[222:225], v[76:79]
	v_mfma_f32_16x16x32_bf16 v[72:75], v[162:165], v[222:225], v[72:75]
	v_mfma_f32_16x16x32_bf16 v[68:71], v[132:135], v[230:233], v[68:71]
	v_mfma_f32_16x16x32_bf16 v[64:67], v[162:165], v[230:233], v[64:67]
	s_setprio 0
	s_setprio 1
	v_mfma_f32_16x16x32_bf16 v[28:31], v[166:169], v[202:205], v[28:31]
	v_mfma_f32_16x16x32_bf16 v[24:27], v[194:197], v[202:205], v[24:27]
	v_mfma_f32_16x16x32_bf16 v[20:23], v[166:169], v[210:213], v[20:23]
	v_mfma_f32_16x16x32_bf16 v[16:19], v[194:197], v[210:213], v[16:19]
	v_mfma_f32_16x16x32_bf16 v[12:15], v[166:169], v[218:221], v[12:15]
	v_mfma_f32_16x16x32_bf16 v[8:11], v[194:197], v[218:221], v[8:11]
	v_mfma_f32_16x16x32_bf16 v[4:7], v[166:169], v[226:229], v[4:7]
	v_mfma_f32_16x16x32_bf16 v[0:3], v[194:197], v[226:229], v[0:3]
	v_mfma_f32_16x16x32_bf16 v[28:31], v[170:173], v[206:209], v[28:31]
	v_mfma_f32_16x16x32_bf16 v[24:27], v[198:201], v[206:209], v[24:27]
	v_mfma_f32_16x16x32_bf16 v[20:23], v[170:173], v[214:217], v[20:23]
	v_mfma_f32_16x16x32_bf16 v[16:19], v[198:201], v[214:217], v[16:19]
	v_mfma_f32_16x16x32_bf16 v[12:15], v[170:173], v[222:225], v[12:15]
	v_mfma_f32_16x16x32_bf16 v[8:11], v[198:201], v[222:225], v[8:11]
	v_mfma_f32_16x16x32_bf16 v[4:7], v[170:173], v[230:233], v[4:7]
	v_mfma_f32_16x16x32_bf16 v[0:3], v[198:201], v[230:233], v[0:3]
	s_setprio 0
	s_barrier
	s_add_i32 s66, s66, 2
	s_add_u32 s8, s8, 0x100
	s_addc_u32 s9, s9, 0
	s_add_u32 s41, s41, 0x100
	s_addc_u32 s57, s57, 0
	s_cmp_gt_u32 s66, 29
	s_cbranch_scc0 .LBB0_195
	s_and_b64 vcc, exec, s[16:17]
	s_cbranch_vccz .LBB0_198
	s_barrier

.LBB0_591:
	v_lshl_add_u32 v146, s6, 8, v152
	v_ashrrev_i32_e32 v147, 31, v146
	v_lshl_add_u64 v[148:149], v[146:147], 2, s[8:9]
	global_load_dword v150, v[148:149], off
	global_load_dword v228, v[148:149], off offset:64
	global_load_dword v229, v[148:149], off offset:128
	global_load_dword v230, v[148:149], off offset:192
	global_load_dword v231, v[148:149], off offset:512
	global_load_dword v232, v[148:149], off offset:576
	global_load_dword v233, v[148:149], off offset:640
	global_load_dword v234, v[148:149], off offset:704
	s_add_i32 s2, s75, -6
	s_cmp_lt_u32 s2, 6
	s_cselect_b64 s[2:3], -1, 0
	s_cmp_gt_i32 s75, 13
	s_cselect_b64 s[6:7], -1, 0
	s_or_b64 s[2:3], s[6:7], s[2:3]
	v_cndmask_b32_e64 v151, 0, 1, s[2:3]
	v_cmp_ne_u32_e64 s[6:7], 1, v151
	s_andn2_b64 vcc, exec, s[2:3]
	s_waitcnt vmcnt(0)
	v_fmamk_f32 v150, v150, 0x3a000000, v157
	v_rsq_f32_e32 v150, v150
	s_nop 0
	v_pk_mul_f32 v[126:127], v[126:127], v[150:151] op_sel_hi:[1,0]
	v_pk_mul_f32 v[124:125], v[124:125], v[150:151] op_sel_hi:[1,0]
	v_pk_mul_f32 v[122:123], v[122:123], v[150:151] op_sel_hi:[1,0]
	v_pk_mul_f32 v[120:121], v[120:121], v[150:151] op_sel_hi:[1,0]
	s_cbranch_vccnz .LBB0_593
	v_mul_f32_e32 v151, 0xbfb8aa3b, v124
	v_exp_f32_e32 v151, v151
	v_mul_f32_e32 v158, 0xbfb8aa3b, v125
	v_mul_f32_e32 v159, 0xbfb8aa3b, v126
	v_exp_f32_e32 v160, v158
	v_exp_f32_e32 v161, v159
	v_add_f32_e32 v151, 1.0, v151
	v_rcp_f32_e32 v158, v151
	v_add_f32_e32 v151, 1.0, v160
	v_mul_f32_e32 v160, 0xbfb8aa3b, v127
	v_rcp_f32_e32 v159, v151
	v_add_f32_e32 v151, 1.0, v161
	v_exp_f32_e32 v161, v160
	v_mul_f32_e32 v160, 0xbfb8aa3b, v120
	v_exp_f32_e32 v162, v160
	v_rcp_f32_e32 v160, v151
	v_add_f32_e32 v151, 1.0, v161
	v_rcp_f32_e32 v161, v151
	v_add_f32_e32 v151, 1.0, v162
	v_mul_f32_e32 v163, 0xbfb8aa3b, v122
	v_rcp_f32_e32 v162, v151
	v_mul_f32_e32 v151, 0xbfb8aa3b, v121
	v_exp_f32_e32 v163, v163
	v_mul_f32_e32 v164, 0xbfb8aa3b, v123
	v_exp_f32_e32 v151, v151
	v_exp_f32_e32 v165, v164
	v_add_f32_e32 v163, 1.0, v163
	v_rcp_f32_e32 v164, v163
	v_add_f32_e32 v151, 1.0, v151
	v_add_f32_e32 v163, 1.0, v165
	v_rcp_f32_e32 v165, v163
	v_rcp_f32_e32 v163, v151
	v_pk_mul_f32 v[126:127], v[126:127], v[160:161]
	v_pk_mul_f32 v[124:125], v[124:125], v[158:159]
	v_pk_mul_f32 v[122:123], v[122:123], v[164:165]
	v_pk_mul_f32 v[120:121], v[120:121], v[162:163]

.LBB0_595:
	v_cvt_pk_bf16_f32 v116, v116, v117
	v_cvt_pk_bf16_f32 v117, v118, v119
	s_nop 0
	v_cvt_pk_bf16_f32 v118, v112, v113
	v_cvt_pk_bf16_f32 v119, v114, v115
	global_store_dwordx4 v[120:121], v[116:119], off offset:256
	s_nop 0
	s_and_b64 vcc, exec, s[6:7]
	s_nop 0
	v_fmamk_f32 v112, v228, 0x3a000000, v157
	v_rsq_f32_e32 v112, v112
	s_nop 0
	v_pk_mul_f32 v[110:111], v[110:111], v[112:113] op_sel_hi:[1,0]
	v_pk_mul_f32 v[108:109], v[108:109], v[112:113] op_sel_hi:[1,0]
	v_pk_mul_f32 v[106:107], v[106:107], v[112:113] op_sel_hi:[1,0]
	v_pk_mul_f32 v[104:105], v[104:105], v[112:113] op_sel_hi:[1,0]
	s_cbranch_vccnz .LBB0_597
	v_mul_f32_e32 v113, 0xbfb8aa3b, v108
	v_exp_f32_e32 v113, v113
	v_mul_f32_e32 v114, 0xbfb8aa3b, v109
	v_mul_f32_e32 v115, 0xbfb8aa3b, v110
	v_exp_f32_e32 v116, v114
	v_exp_f32_e32 v117, v115
	v_add_f32_e32 v113, 1.0, v113
	v_rcp_f32_e32 v114, v113
	v_add_f32_e32 v113, 1.0, v116
	v_mul_f32_e32 v116, 0xbfb8aa3b, v111
	v_rcp_f32_e32 v115, v113
	v_add_f32_e32 v113, 1.0, v117
	v_exp_f32_e32 v117, v116
	v_mul_f32_e32 v116, 0xbfb8aa3b, v104
	v_exp_f32_e32 v118, v116
	v_rcp_f32_e32 v116, v113
	v_add_f32_e32 v113, 1.0, v117
	v_rcp_f32_e32 v117, v113
	v_add_f32_e32 v113, 1.0, v118
	v_mul_f32_e32 v119, 0xbfb8aa3b, v106
	v_rcp_f32_e32 v118, v113
	v_mul_f32_e32 v113, 0xbfb8aa3b, v105
	v_exp_f32_e32 v119, v119
	v_mul_f32_e32 v120, 0xbfb8aa3b, v107
	v_exp_f32_e32 v113, v113
	v_exp_f32_e32 v121, v120
	v_add_f32_e32 v119, 1.0, v119
	v_rcp_f32_e32 v120, v119
	v_add_f32_e32 v113, 1.0, v113
	v_add_f32_e32 v119, 1.0, v121
	v_rcp_f32_e32 v121, v119
	v_rcp_f32_e32 v119, v113
	v_pk_mul_f32 v[110:111], v[110:111], v[116:117]
	v_pk_mul_f32 v[108:109], v[108:109], v[114:115]
	v_pk_mul_f32 v[106:107], v[106:107], v[120:121]
	v_pk_mul_f32 v[104:105], v[104:105], v[118:119]

.LBB0_599:
	v_cvt_pk_bf16_f32 v100, v100, v101
	v_cvt_pk_bf16_f32 v101, v102, v103
	s_nop 0
	v_cvt_pk_bf16_f32 v102, v96, v97
	v_cvt_pk_bf16_f32 v103, v98, v99
	global_store_dwordx4 v[104:105], v[100:103], off offset:256
	s_nop 0
	s_and_b64 vcc, exec, s[6:7]
	s_nop 0
	v_fmamk_f32 v96, v229, 0x3a000000, v157
	v_rsq_f32_e32 v96, v96
	s_nop 0
	v_pk_mul_f32 v[94:95], v[94:95], v[96:97] op_sel_hi:[1,0]
	v_pk_mul_f32 v[92:93], v[92:93], v[96:97] op_sel_hi:[1,0]
	v_pk_mul_f32 v[90:91], v[90:91], v[96:97] op_sel_hi:[1,0]
	v_pk_mul_f32 v[88:89], v[88:89], v[96:97] op_sel_hi:[1,0]
	s_cbranch_vccnz .LBB0_601
	v_mul_f32_e32 v97, 0xbfb8aa3b, v92
	v_exp_f32_e32 v97, v97
	v_mul_f32_e32 v98, 0xbfb8aa3b, v93
	v_mul_f32_e32 v99, 0xbfb8aa3b, v94
	v_exp_f32_e32 v100, v98
	v_exp_f32_e32 v101, v99
	v_add_f32_e32 v97, 1.0, v97
	v_rcp_f32_e32 v98, v97
	v_add_f32_e32 v97, 1.0, v100
	v_mul_f32_e32 v100, 0xbfb8aa3b, v95
	v_rcp_f32_e32 v99, v97
	v_add_f32_e32 v97, 1.0, v101
	v_exp_f32_e32 v101, v100
	v_mul_f32_e32 v100, 0xbfb8aa3b, v88
	v_exp_f32_e32 v102, v100
	v_rcp_f32_e32 v100, v97
	v_add_f32_e32 v97, 1.0, v101
	v_rcp_f32_e32 v101, v97
	v_add_f32_e32 v97, 1.0, v102
	v_mul_f32_e32 v103, 0xbfb8aa3b, v90
	v_rcp_f32_e32 v102, v97
	v_mul_f32_e32 v97, 0xbfb8aa3b, v89
	v_exp_f32_e32 v103, v103
	v_mul_f32_e32 v104, 0xbfb8aa3b, v91
	v_exp_f32_e32 v97, v97
	v_exp_f32_e32 v105, v104
	v_add_f32_e32 v103, 1.0, v103
	v_rcp_f32_e32 v104, v103
	v_add_f32_e32 v97, 1.0, v97
	v_add_f32_e32 v103, 1.0, v105
	v_rcp_f32_e32 v105, v103
	v_rcp_f32_e32 v103, v97
	v_pk_mul_f32 v[94:95], v[94:95], v[100:101]
	v_pk_mul_f32 v[92:93], v[92:93], v[98:99]
	v_pk_mul_f32 v[90:91], v[90:91], v[104:105]
	v_pk_mul_f32 v[88:89], v[88:89], v[102:103]

.LBB0_603:
	v_cvt_pk_bf16_f32 v84, v84, v85
	v_cvt_pk_bf16_f32 v85, v86, v87
	s_nop 0
	v_cvt_pk_bf16_f32 v86, v80, v81
	v_cvt_pk_bf16_f32 v87, v82, v83
	global_store_dwordx4 v[88:89], v[84:87], off offset:256
	s_nop 0
	s_and_b64 vcc, exec, s[6:7]
	s_nop 0
	v_fmamk_f32 v80, v230, 0x3a000000, v157
	v_rsq_f32_e32 v80, v80
	s_nop 0
	v_pk_mul_f32 v[78:79], v[78:79], v[80:81] op_sel_hi:[1,0]
	v_pk_mul_f32 v[76:77], v[76:77], v[80:81] op_sel_hi:[1,0]
	v_pk_mul_f32 v[74:75], v[74:75], v[80:81] op_sel_hi:[1,0]
	v_pk_mul_f32 v[72:73], v[72:73], v[80:81] op_sel_hi:[1,0]
	s_cbranch_vccnz .LBB0_605
	v_mul_f32_e32 v81, 0xbfb8aa3b, v76
	v_exp_f32_e32 v81, v81
	v_mul_f32_e32 v82, 0xbfb8aa3b, v77
	v_mul_f32_e32 v83, 0xbfb8aa3b, v78
	v_exp_f32_e32 v84, v82
	v_exp_f32_e32 v85, v83
	v_add_f32_e32 v81, 1.0, v81
	v_rcp_f32_e32 v82, v81
	v_add_f32_e32 v81, 1.0, v84
	v_mul_f32_e32 v84, 0xbfb8aa3b, v79
	v_rcp_f32_e32 v83, v81
	v_add_f32_e32 v81, 1.0, v85
	v_exp_f32_e32 v85, v84
	v_mul_f32_e32 v84, 0xbfb8aa3b, v72
	v_exp_f32_e32 v86, v84
	v_rcp_f32_e32 v84, v81
	v_add_f32_e32 v81, 1.0, v85
	v_rcp_f32_e32 v85, v81
	v_add_f32_e32 v81, 1.0, v86
	v_mul_f32_e32 v87, 0xbfb8aa3b, v74
	v_rcp_f32_e32 v86, v81
	v_mul_f32_e32 v81, 0xbfb8aa3b, v73
	v_exp_f32_e32 v87, v87
	v_mul_f32_e32 v88, 0xbfb8aa3b, v75
	v_exp_f32_e32 v81, v81
	v_exp_f32_e32 v89, v88
	v_add_f32_e32 v87, 1.0, v87
	v_rcp_f32_e32 v88, v87
	v_add_f32_e32 v81, 1.0, v81
	v_add_f32_e32 v87, 1.0, v89
	v_rcp_f32_e32 v89, v87
	v_rcp_f32_e32 v87, v81
	v_pk_mul_f32 v[78:79], v[78:79], v[84:85]
	v_pk_mul_f32 v[76:77], v[76:77], v[82:83]
	v_pk_mul_f32 v[74:75], v[74:75], v[88:89]
	v_pk_mul_f32 v[72:73], v[72:73], v[86:87]

.LBB0_607:
	v_cvt_pk_bf16_f32 v68, v68, v69
	v_cvt_pk_bf16_f32 v69, v70, v71
	s_nop 0
	v_cvt_pk_bf16_f32 v70, v64, v65
	v_cvt_pk_bf16_f32 v71, v66, v67
	global_store_dwordx4 v[72:73], v[68:71], off offset:256
	s_nop 0
	s_and_b64 vcc, exec, s[6:7]
	s_nop 0
	v_fmamk_f32 v64, v231, 0x3a000000, v157
	v_rsq_f32_e32 v64, v64
	s_nop 0
	v_pk_mul_f32 v[62:63], v[62:63], v[64:65] op_sel_hi:[1,0]
	v_pk_mul_f32 v[60:61], v[60:61], v[64:65] op_sel_hi:[1,0]
	v_pk_mul_f32 v[58:59], v[58:59], v[64:65] op_sel_hi:[1,0]
	v_pk_mul_f32 v[56:57], v[56:57], v[64:65] op_sel_hi:[1,0]
	s_cbranch_vccnz .LBB0_609
	v_mul_f32_e32 v65, 0xbfb8aa3b, v60
	v_exp_f32_e32 v65, v65
	v_mul_f32_e32 v66, 0xbfb8aa3b, v61
	v_mul_f32_e32 v67, 0xbfb8aa3b, v62
	v_exp_f32_e32 v68, v66
	v_exp_f32_e32 v69, v67
	v_add_f32_e32 v65, 1.0, v65
	v_rcp_f32_e32 v66, v65
	v_add_f32_e32 v65, 1.0, v68
	v_mul_f32_e32 v68, 0xbfb8aa3b, v63
	v_rcp_f32_e32 v67, v65
	v_add_f32_e32 v65, 1.0, v69
	v_exp_f32_e32 v69, v68
	v_mul_f32_e32 v68, 0xbfb8aa3b, v56
	v_exp_f32_e32 v70, v68
	v_rcp_f32_e32 v68, v65
	v_add_f32_e32 v65, 1.0, v69
	v_rcp_f32_e32 v69, v65
	v_add_f32_e32 v65, 1.0, v70
	v_mul_f32_e32 v71, 0xbfb8aa3b, v58
	v_rcp_f32_e32 v70, v65
	v_mul_f32_e32 v65, 0xbfb8aa3b, v57
	v_exp_f32_e32 v71, v71
	v_mul_f32_e32 v72, 0xbfb8aa3b, v59
	v_exp_f32_e32 v65, v65
	v_exp_f32_e32 v73, v72
	v_add_f32_e32 v71, 1.0, v71
	v_rcp_f32_e32 v72, v71
	v_add_f32_e32 v65, 1.0, v65
	v_add_f32_e32 v71, 1.0, v73
	v_rcp_f32_e32 v73, v71
	v_rcp_f32_e32 v71, v65
	v_pk_mul_f32 v[62:63], v[62:63], v[68:69]
	v_pk_mul_f32 v[60:61], v[60:61], v[66:67]
	v_pk_mul_f32 v[58:59], v[58:59], v[72:73]
	v_pk_mul_f32 v[56:57], v[56:57], v[70:71]

.LBB0_611:
	v_lshl_add_u64 v[56:57], v[56:57], 0, s[18:19]
	v_cvt_pk_bf16_f32 v52, v52, v53
	v_cvt_pk_bf16_f32 v53, v54, v55
	v_cvt_pk_bf16_f32 v54, v48, v49
	v_cvt_pk_bf16_f32 v55, v50, v51
	global_store_dwordx4 v[56:57], v[52:55], off offset:256
	s_nop 0
	s_and_b64 vcc, exec, s[6:7]
	s_nop 0
	v_fmamk_f32 v48, v232, 0x3a000000, v157
	v_rsq_f32_e32 v48, v48
	s_nop 0
	v_pk_mul_f32 v[46:47], v[46:47], v[48:49] op_sel_hi:[1,0]
	v_pk_mul_f32 v[44:45], v[44:45], v[48:49] op_sel_hi:[1,0]
	v_pk_mul_f32 v[42:43], v[42:43], v[48:49] op_sel_hi:[1,0]
	v_pk_mul_f32 v[40:41], v[40:41], v[48:49] op_sel_hi:[1,0]
	s_cbranch_vccnz .LBB0_613
	v_mul_f32_e32 v49, 0xbfb8aa3b, v44
	v_exp_f32_e32 v49, v49
	v_mul_f32_e32 v50, 0xbfb8aa3b, v45
	v_mul_f32_e32 v51, 0xbfb8aa3b, v46
	v_exp_f32_e32 v52, v50
	v_exp_f32_e32 v53, v51
	v_add_f32_e32 v49, 1.0, v49
	v_rcp_f32_e32 v50, v49
	v_add_f32_e32 v49, 1.0, v52
	v_mul_f32_e32 v52, 0xbfb8aa3b, v47
	v_rcp_f32_e32 v51, v49
	v_add_f32_e32 v49, 1.0, v53
	v_exp_f32_e32 v53, v52
	v_mul_f32_e32 v52, 0xbfb8aa3b, v40
	v_exp_f32_e32 v54, v52
	v_rcp_f32_e32 v52, v49
	v_add_f32_e32 v49, 1.0, v53
	v_rcp_f32_e32 v53, v49
	v_add_f32_e32 v49, 1.0, v54
	v_mul_f32_e32 v55, 0xbfb8aa3b, v42
	v_rcp_f32_e32 v54, v49
	v_mul_f32_e32 v49, 0xbfb8aa3b, v41
	v_exp_f32_e32 v55, v55
	v_mul_f32_e32 v56, 0xbfb8aa3b, v43
	v_exp_f32_e32 v49, v49
	v_exp_f32_e32 v57, v56
	v_add_f32_e32 v55, 1.0, v55
	v_rcp_f32_e32 v56, v55
	v_add_f32_e32 v49, 1.0, v49
	v_add_f32_e32 v55, 1.0, v57
	v_rcp_f32_e32 v57, v55
	v_rcp_f32_e32 v55, v49
	v_pk_mul_f32 v[46:47], v[46:47], v[52:53]
	v_pk_mul_f32 v[44:45], v[44:45], v[50:51]
	v_pk_mul_f32 v[42:43], v[42:43], v[56:57]
	v_pk_mul_f32 v[40:41], v[40:41], v[54:55]

.LBB0_615:
	v_lshl_add_u64 v[40:41], v[40:41], 0, s[20:21]
	v_cvt_pk_bf16_f32 v36, v36, v37
	v_cvt_pk_bf16_f32 v37, v38, v39
	v_cvt_pk_bf16_f32 v38, v32, v33
	v_cvt_pk_bf16_f32 v39, v34, v35
	global_store_dwordx4 v[40:41], v[36:39], off offset:256
	s_nop 0
	s_and_b64 vcc, exec, s[6:7]
	s_nop 0
	v_fmamk_f32 v32, v233, 0x3a000000, v157
	v_rsq_f32_e32 v32, v32
	s_nop 0
	v_pk_mul_f32 v[30:31], v[30:31], v[32:33] op_sel_hi:[1,0]
	v_pk_mul_f32 v[28:29], v[28:29], v[32:33] op_sel_hi:[1,0]
	v_pk_mul_f32 v[26:27], v[26:27], v[32:33] op_sel_hi:[1,0]
	v_pk_mul_f32 v[24:25], v[24:25], v[32:33] op_sel_hi:[1,0]
	s_cbranch_vccnz .LBB0_617
	v_mul_f32_e32 v33, 0xbfb8aa3b, v28
	v_exp_f32_e32 v33, v33
	v_mul_f32_e32 v34, 0xbfb8aa3b, v29
	v_mul_f32_e32 v35, 0xbfb8aa3b, v30
	v_exp_f32_e32 v36, v34
	v_exp_f32_e32 v37, v35
	v_add_f32_e32 v33, 1.0, v33
	v_rcp_f32_e32 v34, v33
	v_add_f32_e32 v33, 1.0, v36
	v_mul_f32_e32 v36, 0xbfb8aa3b, v31
	v_rcp_f32_e32 v35, v33
	v_add_f32_e32 v33, 1.0, v37
	v_exp_f32_e32 v37, v36
	v_mul_f32_e32 v36, 0xbfb8aa3b, v24
	v_exp_f32_e32 v38, v36
	v_rcp_f32_e32 v36, v33
	v_add_f32_e32 v33, 1.0, v37
	v_rcp_f32_e32 v37, v33
	v_add_f32_e32 v33, 1.0, v38
	v_mul_f32_e32 v39, 0xbfb8aa3b, v26
	v_rcp_f32_e32 v38, v33
	v_mul_f32_e32 v33, 0xbfb8aa3b, v25
	v_exp_f32_e32 v39, v39
	v_mul_f32_e32 v40, 0xbfb8aa3b, v27
	v_exp_f32_e32 v33, v33
	v_exp_f32_e32 v41, v40
	v_add_f32_e32 v39, 1.0, v39
	v_rcp_f32_e32 v40, v39
	v_add_f32_e32 v33, 1.0, v33
	v_add_f32_e32 v39, 1.0, v41
	v_rcp_f32_e32 v41, v39
	v_rcp_f32_e32 v39, v33
	v_pk_mul_f32 v[30:31], v[30:31], v[36:37]
	v_pk_mul_f32 v[28:29], v[28:29], v[34:35]
	v_pk_mul_f32 v[26:27], v[26:27], v[40:41]
	v_pk_mul_f32 v[24:25], v[24:25], v[38:39]

.LBB0_619:
	v_lshl_add_u64 v[24:25], v[24:25], 0, s[24:25]
	v_cvt_pk_bf16_f32 v20, v20, v21
	v_cvt_pk_bf16_f32 v21, v22, v23
	v_cvt_pk_bf16_f32 v22, v16, v17
	v_cvt_pk_bf16_f32 v23, v18, v19
	global_store_dwordx4 v[24:25], v[20:23], off offset:256
	s_nop 0
	s_and_b64 vcc, exec, s[6:7]
	s_nop 0
	v_fmamk_f32 v16, v234, 0x3a000000, v157
	v_rsq_f32_e32 v16, v16
	s_nop 0
	v_pk_mul_f32 v[14:15], v[14:15], v[16:17] op_sel_hi:[1,0]
	v_pk_mul_f32 v[12:13], v[12:13], v[16:17] op_sel_hi:[1,0]
	v_pk_mul_f32 v[10:11], v[10:11], v[16:17] op_sel_hi:[1,0]
	v_pk_mul_f32 v[8:9], v[8:9], v[16:17] op_sel_hi:[1,0]
	s_cbranch_vccnz .LBB0_621
	v_mul_f32_e32 v17, 0xbfb8aa3b, v12
	v_exp_f32_e32 v17, v17
	v_mul_f32_e32 v18, 0xbfb8aa3b, v13
	v_mul_f32_e32 v19, 0xbfb8aa3b, v14
	v_exp_f32_e32 v20, v18
	v_exp_f32_e32 v21, v19
	v_add_f32_e32 v17, 1.0, v17
	v_rcp_f32_e32 v18, v17
	v_add_f32_e32 v17, 1.0, v20
	v_mul_f32_e32 v20, 0xbfb8aa3b, v15
	v_rcp_f32_e32 v19, v17
	v_add_f32_e32 v17, 1.0, v21
	v_exp_f32_e32 v21, v20
	v_mul_f32_e32 v20, 0xbfb8aa3b, v8
	v_exp_f32_e32 v22, v20
	v_rcp_f32_e32 v20, v17
	v_add_f32_e32 v17, 1.0, v21
	v_rcp_f32_e32 v21, v17
	v_add_f32_e32 v17, 1.0, v22
	v_mul_f32_e32 v23, 0xbfb8aa3b, v10
	v_rcp_f32_e32 v22, v17
	v_mul_f32_e32 v17, 0xbfb8aa3b, v9
	v_exp_f32_e32 v23, v23
	v_mul_f32_e32 v24, 0xbfb8aa3b, v11
	v_exp_f32_e32 v17, v17
	v_exp_f32_e32 v25, v24
	v_add_f32_e32 v23, 1.0, v23
	v_rcp_f32_e32 v24, v23
	v_add_f32_e32 v17, 1.0, v17
	v_add_f32_e32 v23, 1.0, v25
	v_rcp_f32_e32 v25, v23
	v_rcp_f32_e32 v23, v17
	v_pk_mul_f32 v[14:15], v[14:15], v[20:21]
	v_pk_mul_f32 v[12:13], v[12:13], v[18:19]
	v_pk_mul_f32 v[10:11], v[10:11], v[24:25]
	v_pk_mul_f32 v[8:9], v[8:9], v[22:23]

.LBB0_700:
	v_lshl_or_b32 v80, s6, 7, v177
	v_ashrrev_i32_e32 v81, 31, v80
	v_lshlrev_b64 v[82:83], 2, v[80:81]
	v_lshl_add_u64 v[156:157], s[58:59], 0, v[82:83]
	global_load_dwordx4 v[96:99], v[156:157], off
	v_lshl_add_u32 v179, s7, 8, v175
	v_mov_b64_e32 v[164:165], s[36:37]
	v_mad_i64_i32 v[152:153], s[30:31], v179, s96, v[164:165]
	v_lshlrev_b64 v[166:167], 1, v[80:81]
	v_lshl_add_u64 v[158:159], s[62:63], 0, v[82:83]
	v_lshl_add_u64 v[160:161], v[152:153], 0, v[166:167]
	v_lshl_add_u64 v[162:163], s[40:41], 0, v[82:83]
	global_load_dwordx4 v[88:91], v[158:159], off
	global_load_dwordx2 v[170:171], v[160:161], off
	s_mov_b64 s[74:75], 0xc000
	s_mov_b64 s[76:77], 0x60000
	v_lshl_add_u64 v[222:223], v[160:161], 0, s[74:75]
	v_lshl_add_u64 v[224:225], v[222:223], 0, s[74:75]
	v_lshl_add_u64 v[226:227], v[224:225], 0, s[74:75]
	v_lshl_add_u64 v[228:229], v[160:161], 0, s[76:77]
	v_lshl_add_u64 v[230:231], v[228:229], 0, s[74:75]
	v_lshl_add_u64 v[232:233], v[230:231], 0, s[74:75]
	v_lshl_add_u64 v[234:235], v[232:233], 0, s[74:75]
	global_load_dwordx2 v[190:191], v[222:223], off
	global_load_dwordx2 v[192:193], v[224:225], off
	global_load_dwordx2 v[194:195], v[226:227], off
	global_load_dwordx2 v[196:197], v[228:229], off
	global_load_dwordx2 v[198:199], v[230:231], off
	global_load_dwordx2 v[200:201], v[232:233], off
	global_load_dwordx2 v[202:203], v[234:235], off
	global_load_dwordx2 v[204:205], v[222:223], off offset:8
	global_load_dwordx2 v[206:207], v[224:225], off offset:8
	global_load_dwordx2 v[208:209], v[226:227], off offset:8
	global_load_dwordx2 v[210:211], v[228:229], off offset:8
	global_load_dwordx2 v[212:213], v[230:231], off offset:8
	global_load_dwordx2 v[214:215], v[232:233], off offset:8
	global_load_dwordx2 v[216:217], v[234:235], off offset:8
	global_load_dwordx4 v[80:83], v[162:163], off
	v_ashrrev_i32_e32 v152, 31, v179
	s_ashr_i32 s7, s6, 31
	v_alignbit_b32 v154, v152, v179, 11
	v_lshrrev_b32_e32 v168, 11, v152
	v_mad_u64_u32 v[154:155], s[30:31], v154, 12, s[6:7]
	v_mad_u32_u24 v155, v168, 12, v155
	v_lshlrev_b32_e32 v140, 9, v179
	v_lshlrev_b64 v[154:155], 20, v[154:155]
	v_and_b32_e32 v140, 0xf9e00, v140
	v_lshl_add_u64 v[168:169], s[38:39], 0, v[154:155]
	v_lshl_add_u64 v[154:155], v[168:169], 0, v[140:141]
	v_mov_b32_e32 v151, v141
	v_or_b32_e32 v180, 16, v179
	v_lshl_add_u64 v[154:155], v[154:155], 0, s[44:45]
	v_mad_i64_i32 v[152:153], s[30:31], v180, s96, v[164:165]
	v_lshl_add_u64 v[154:155], v[154:155], 0, v[150:151]
	v_lshl_add_u64 v[152:153], v[152:153], 0, v[166:167]
	s_cmp_eq_u32 s5, 7
	s_mov_b64 s[64:65], -1
	s_waitcnt vmcnt(0)
	v_pk_add_f32 v[138:139], v[138:139], v[98:99]
	v_pk_add_f32 v[136:137], v[136:137], v[96:97]
	v_mul_f32_e32 v138, 0xbfb8aa3b, v138
	v_mul_f32_e32 v136, 0xbfb8aa3b, v136
	v_mul_f32_e32 v137, 0xbfb8aa3b, v137
	v_mul_f32_e32 v139, 0xbfb8aa3b, v139
	v_exp_f32_e32 v136, v136
	v_exp_f32_e32 v137, v137
	v_exp_f32_e32 v138, v138
	v_exp_f32_e32 v139, v139
	v_add_f32_e32 v136, 1.0, v136
	v_add_f32_e32 v137, 1.0, v137
	v_add_f32_e32 v138, 1.0, v138
	v_add_f32_e32 v139, 1.0, v139
	v_rcp_f32_e32 v136, v136
	v_rcp_f32_e32 v137, v137
	v_rcp_f32_e32 v138, v138
	v_rcp_f32_e32 v139, v139
	v_pk_add_f32 v[134:135], v[134:135], v[90:91]
	v_pk_add_f32 v[132:133], v[132:133], v[88:89]
	v_mul_f32_e32 v136, v80, v136
	v_mul_f32_e32 v137, v81, v137
	v_mul_f32_e32 v138, v82, v138
	v_mul_f32_e32 v139, v83, v139
	v_mul_f32_e32 v132, 0xbfb8aa3b, v132
	v_mul_f32_e32 v133, 0xbfb8aa3b, v133
	v_mul_f32_e32 v134, 0xbfb8aa3b, v134
	v_mul_f32_e32 v135, 0xbfb8aa3b, v135
	v_exp_f32_e32 v182, v136
	v_exp_f32_e32 v183, v137
	v_exp_f32_e32 v184, v138
	v_exp_f32_e32 v185, v139
	v_exp_f32_e32 v132, v132
	v_exp_f32_e32 v133, v133
	v_exp_f32_e32 v134, v134
	v_exp_f32_e32 v135, v135
	v_fma_f32 v182, -v182, v182, 1.0
	v_fma_f32 v183, -v183, v183, 1.0
	v_fma_f32 v184, -v184, v184, 1.0
	v_fma_f32 v185, -v185, v185, 1.0
	v_add_f32_e32 v132, 1.0, v132
	v_add_f32_e32 v133, 1.0, v133
	v_add_f32_e32 v134, 1.0, v134
	v_add_f32_e32 v135, 1.0, v135
	v_max_f32_e32 v182, 0, v182
	v_max_f32_e32 v183, 0, v183
	v_max_f32_e32 v184, 0, v184
	v_max_f32_e32 v185, 0, v185
	v_rcp_f32_e32 v132, v132
	v_rcp_f32_e32 v133, v133
	v_rcp_f32_e32 v134, v134
	v_rcp_f32_e32 v135, v135
	v_sqrt_f32_e32 v182, v182
	v_sqrt_f32_e32 v183, v183
	v_sqrt_f32_e32 v184, v184
	v_sqrt_f32_e32 v185, v185
	v_lshlrev_b32_e32 v140, 16, v170
	v_and_b32_e32 v170, 0xffff0000, v170
	v_lshlrev_b32_e32 v181, 16, v171
	v_and_b32_e32 v171, 0xffff0000, v171
	v_mul_f32_e32 v132, v132, v182
	v_mul_f32_e32 v133, v133, v183
	v_mul_f32_e32 v134, v134, v184
	v_mul_f32_e32 v135, v135, v185
	v_mul_f32_e32 v132, v132, v140
	v_mul_f32_e32 v133, v133, v170
	v_mul_f32_e32 v134, v134, v181
	v_mul_f32_e32 v135, v135, v171
	v_cvt_pk_bf16_f32 v132, v136, v132
	v_cvt_pk_bf16_f32 v133, v137, v133
	v_cvt_pk_bf16_f32 v134, v138, v134
	v_cvt_pk_bf16_f32 v135, v139, v135
	global_store_dwordx4 v[154:155], v[132:135], off
	s_nop 0
	v_pk_add_f32 v[130:131], v[130:131], v[98:99]
	v_pk_add_f32 v[128:129], v[128:129], v[96:97]
	v_mul_f32_e32 v130, 0xbfb8aa3b, v130
	v_mul_f32_e32 v128, 0xbfb8aa3b, v128
	v_mul_f32_e32 v129, 0xbfb8aa3b, v129
	v_mul_f32_e32 v131, 0xbfb8aa3b, v131
	v_exp_f32_e32 v128, v128
	v_exp_f32_e32 v129, v129
	v_exp_f32_e32 v130, v130
	v_exp_f32_e32 v131, v131
	v_add_f32_e32 v128, 1.0, v128
	v_add_f32_e32 v129, 1.0, v129
	v_add_f32_e32 v130, 1.0, v130
	v_add_f32_e32 v131, 1.0, v131
	v_rcp_f32_e32 v128, v128
	v_rcp_f32_e32 v129, v129
	v_rcp_f32_e32 v130, v130
	v_rcp_f32_e32 v131, v131
	v_lshlrev_b32_e32 v134, 9, v180
	v_and_b32_e32 v140, 0xffe00, v134
	v_pk_add_f32 v[126:127], v[126:127], v[90:91]
	v_pk_add_f32 v[124:125], v[124:125], v[88:89]
	v_mul_f32_e32 v128, v80, v128
	v_mul_f32_e32 v129, v81, v129
	v_mul_f32_e32 v130, v82, v130
	v_mul_f32_e32 v131, v83, v131
	v_lshl_add_u64 v[134:135], v[168:169], 0, v[140:141]
	v_mul_f32_e32 v124, 0xbfb8aa3b, v124
	v_mul_f32_e32 v125, 0xbfb8aa3b, v125
	v_mul_f32_e32 v126, 0xbfb8aa3b, v126
	v_mul_f32_e32 v127, 0xbfb8aa3b, v127
	v_exp_f32_e32 v139, v128
	v_exp_f32_e32 v140, v129
	v_exp_f32_e32 v170, v130
	v_exp_f32_e32 v171, v131
	v_exp_f32_e32 v124, v124
	v_exp_f32_e32 v125, v125
	v_exp_f32_e32 v126, v126
	v_exp_f32_e32 v127, v127
	v_fma_f32 v139, -v139, v139, 1.0
	v_fma_f32 v140, -v140, v140, 1.0
	v_fma_f32 v170, -v170, v170, 1.0
	v_fma_f32 v171, -v171, v171, 1.0
	v_add_f32_e32 v124, 1.0, v124
	v_add_f32_e32 v125, 1.0, v125
	v_add_f32_e32 v126, 1.0, v126
	v_add_f32_e32 v127, 1.0, v127
	v_max_f32_e32 v139, 0, v139
	v_max_f32_e32 v140, 0, v140
	v_max_f32_e32 v170, 0, v170
	v_max_f32_e32 v171, 0, v171
	v_rcp_f32_e32 v124, v124
	v_rcp_f32_e32 v125, v125
	v_rcp_f32_e32 v126, v126
	v_rcp_f32_e32 v127, v127
	v_sqrt_f32_e32 v139, v139
	v_sqrt_f32_e32 v140, v140
	v_sqrt_f32_e32 v170, v170
	v_sqrt_f32_e32 v171, v171
	v_or_b32_e32 v138, 32, v179
	v_lshl_add_u64 v[134:135], v[134:135], 0, s[44:45]
	v_mul_f32_e32 v124, v124, v139
	v_mul_f32_e32 v125, v125, v140
	v_mul_f32_e32 v126, v126, v170
	v_mul_f32_e32 v127, v127, v171
	v_mad_i64_i32 v[132:133], s[30:31], v138, s96, v[164:165]
	v_lshl_add_u64 v[134:135], v[134:135], 0, v[150:151]
	v_lshl_add_u64 v[132:133], v[132:133], 0, v[166:167]
	v_pk_add_f32 v[122:123], v[122:123], v[98:99]
	v_pk_add_f32 v[120:121], v[120:121], v[96:97]
	v_mul_f32_e32 v122, 0xbfb8aa3b, v122
	v_mul_f32_e32 v120, 0xbfb8aa3b, v120
	v_mul_f32_e32 v121, 0xbfb8aa3b, v121
	v_mul_f32_e32 v123, 0xbfb8aa3b, v123
	v_exp_f32_e32 v120, v120
	v_exp_f32_e32 v121, v121
	v_exp_f32_e32 v122, v122
	v_exp_f32_e32 v123, v123
	s_nop 0
	v_lshlrev_b32_e32 v139, 16, v190
	v_and_b32_e32 v136, 0xffff0000, v190
	v_lshlrev_b32_e32 v140, 16, v191
	v_and_b32_e32 v137, 0xffff0000, v191
	v_mul_f32_e32 v124, v124, v139
	v_mul_f32_e32 v125, v125, v136
	v_mul_f32_e32 v126, v126, v140
	v_mul_f32_e32 v127, v127, v137
	v_cvt_pk_bf16_f32 v124, v128, v124
	v_cvt_pk_bf16_f32 v125, v129, v125
	v_cvt_pk_bf16_f32 v126, v130, v126
	v_cvt_pk_bf16_f32 v127, v131, v127
	global_store_dwordx4 v[134:135], v[124:127], off
	s_nop 0
	v_add_f32_e32 v120, 1.0, v120
	v_add_f32_e32 v121, 1.0, v121
	v_add_f32_e32 v122, 1.0, v122
	v_add_f32_e32 v123, 1.0, v123
	v_rcp_f32_e32 v120, v120
	v_rcp_f32_e32 v121, v121
	v_rcp_f32_e32 v122, v122
	v_rcp_f32_e32 v123, v123
	v_pk_add_f32 v[118:119], v[118:119], v[90:91]
	v_pk_add_f32 v[116:117], v[116:117], v[88:89]
	v_mul_f32_e32 v120, v80, v120
	v_mul_f32_e32 v121, v81, v121
	v_mul_f32_e32 v122, v82, v122
	v_mul_f32_e32 v123, v83, v123
	v_lshlrev_b32_e32 v126, 9, v138
	v_mul_f32_e32 v116, 0xbfb8aa3b, v116
	v_mul_f32_e32 v117, 0xbfb8aa3b, v117
	v_mul_f32_e32 v118, 0xbfb8aa3b, v118
	v_mul_f32_e32 v119, 0xbfb8aa3b, v119
	v_exp_f32_e32 v131, v120
	v_exp_f32_e32 v136, v121
	v_exp_f32_e32 v137, v122
	v_exp_f32_e32 v138, v123
	v_exp_f32_e32 v116, v116
	v_exp_f32_e32 v117, v117
	v_exp_f32_e32 v118, v118
	v_exp_f32_e32 v119, v119
	v_fma_f32 v131, -v131, v131, 1.0
	v_fma_f32 v136, -v136, v136, 1.0
	v_fma_f32 v137, -v137, v137, 1.0
	v_fma_f32 v138, -v138, v138, 1.0
	v_add_f32_e32 v116, 1.0, v116
	v_add_f32_e32 v117, 1.0, v117
	v_add_f32_e32 v118, 1.0, v118
	v_add_f32_e32 v119, 1.0, v119
	v_max_f32_e32 v131, 0, v131
	v_max_f32_e32 v136, 0, v136
	v_max_f32_e32 v137, 0, v137
	v_max_f32_e32 v138, 0, v138
	v_rcp_f32_e32 v116, v116
	v_rcp_f32_e32 v117, v117
	v_rcp_f32_e32 v118, v118
	v_rcp_f32_e32 v119, v119
	v_sqrt_f32_e32 v131, v131
	v_sqrt_f32_e32 v136, v136
	v_sqrt_f32_e32 v137, v137
	v_sqrt_f32_e32 v138, v138
	v_and_b32_e32 v140, 0xffe00, v126
	v_lshl_add_u64 v[126:127], v[168:169], 0, v[140:141]
	v_or_b32_e32 v130, 48, v179
	v_lshl_add_u64 v[126:127], v[126:127], 0, s[44:45]
	v_mul_f32_e32 v116, v116, v131
	v_mul_f32_e32 v117, v117, v136
	v_mul_f32_e32 v118, v118, v137
	v_mul_f32_e32 v119, v119, v138
	v_mad_i64_i32 v[124:125], s[30:31], v130, s96, v[164:165]
	v_lshl_add_u64 v[126:127], v[126:127], 0, v[150:151]
	v_lshl_add_u64 v[124:125], v[124:125], 0, v[166:167]
	v_pk_add_f32 v[114:115], v[114:115], v[98:99]
	v_pk_add_f32 v[112:113], v[112:113], v[96:97]
	v_mul_f32_e32 v114, 0xbfb8aa3b, v114
	v_mul_f32_e32 v112, 0xbfb8aa3b, v112
	v_mul_f32_e32 v113, 0xbfb8aa3b, v113
	v_mul_f32_e32 v115, 0xbfb8aa3b, v115
	v_exp_f32_e32 v112, v112
	v_exp_f32_e32 v113, v113
	v_exp_f32_e32 v114, v114
	v_exp_f32_e32 v115, v115
	v_add_f32_e32 v112, 1.0, v112
	v_add_f32_e32 v113, 1.0, v113
	v_add_f32_e32 v114, 1.0, v114
	v_add_f32_e32 v115, 1.0, v115
	v_rcp_f32_e32 v112, v112
	v_rcp_f32_e32 v113, v113
	v_rcp_f32_e32 v114, v114
	v_rcp_f32_e32 v115, v115
	v_pk_add_f32 v[110:111], v[110:111], v[90:91]
	v_pk_add_f32 v[108:109], v[108:109], v[88:89]
	s_nop 0
	v_lshlrev_b32_e32 v131, 16, v192
	v_and_b32_e32 v128, 0xffff0000, v192
	v_lshlrev_b32_e32 v136, 16, v193
	v_and_b32_e32 v129, 0xffff0000, v193
	v_mul_f32_e32 v116, v116, v131
	v_mul_f32_e32 v117, v117, v128
	v_mul_f32_e32 v118, v118, v136
	v_mul_f32_e32 v119, v119, v129
	v_cvt_pk_bf16_f32 v116, v120, v116
	v_cvt_pk_bf16_f32 v117, v121, v117
	v_cvt_pk_bf16_f32 v118, v122, v118
	v_cvt_pk_bf16_f32 v119, v123, v119
	global_store_dwordx4 v[126:127], v[116:119], off
	s_nop 0
	v_mul_f32_e32 v112, v80, v112
	v_mul_f32_e32 v113, v81, v113
	v_mul_f32_e32 v114, v82, v114
	v_mul_f32_e32 v115, v83, v115
	v_lshlrev_b32_e32 v118, 9, v130
	v_mul_f32_e32 v108, 0xbfb8aa3b, v108
	v_mul_f32_e32 v109, 0xbfb8aa3b, v109
	v_mul_f32_e32 v110, 0xbfb8aa3b, v110
	v_mul_f32_e32 v111, 0xbfb8aa3b, v111
	v_exp_f32_e32 v123, v112
	v_exp_f32_e32 v128, v113
	v_exp_f32_e32 v129, v114
	v_exp_f32_e32 v130, v115
	v_exp_f32_e32 v108, v108
	v_exp_f32_e32 v109, v109
	v_exp_f32_e32 v110, v110
	v_exp_f32_e32 v111, v111
	v_fma_f32 v123, -v123, v123, 1.0
	v_fma_f32 v128, -v128, v128, 1.0
	v_fma_f32 v129, -v129, v129, 1.0
	v_fma_f32 v130, -v130, v130, 1.0
	v_add_f32_e32 v108, 1.0, v108
	v_add_f32_e32 v109, 1.0, v109
	v_add_f32_e32 v110, 1.0, v110
	v_add_f32_e32 v111, 1.0, v111
	v_max_f32_e32 v123, 0, v123
	v_max_f32_e32 v128, 0, v128
	v_max_f32_e32 v129, 0, v129
	v_max_f32_e32 v130, 0, v130
	v_rcp_f32_e32 v108, v108
	v_rcp_f32_e32 v109, v109
	v_rcp_f32_e32 v110, v110
	v_rcp_f32_e32 v111, v111
	v_sqrt_f32_e32 v123, v123
	v_sqrt_f32_e32 v128, v128
	v_sqrt_f32_e32 v129, v129
	v_sqrt_f32_e32 v130, v130
	v_and_b32_e32 v140, 0xffe00, v118
	v_lshl_add_u64 v[118:119], v[168:169], 0, v[140:141]
	v_add_u32_e32 v122, 0x80, v179
	v_lshl_add_u64 v[118:119], v[118:119], 0, s[44:45]
	v_mul_f32_e32 v108, v108, v123
	v_mul_f32_e32 v109, v109, v128
	v_mul_f32_e32 v110, v110, v129
	v_mul_f32_e32 v111, v111, v130
	v_mad_i64_i32 v[116:117], s[30:31], v122, s96, v[164:165]
	v_lshl_add_u64 v[118:119], v[118:119], 0, v[150:151]
	v_lshl_add_u64 v[116:117], v[116:117], 0, v[166:167]
	v_pk_add_f32 v[104:105], v[104:105], v[96:97]
	v_pk_add_f32 v[106:107], v[106:107], v[98:99]
	v_mul_f32_e32 v104, 0xbfb8aa3b, v104
	v_mul_f32_e32 v105, 0xbfb8aa3b, v105
	v_mul_f32_e32 v106, 0xbfb8aa3b, v106
	v_mul_f32_e32 v107, 0xbfb8aa3b, v107
	v_exp_f32_e32 v104, v104
	v_exp_f32_e32 v105, v105
	v_exp_f32_e32 v106, v106
	v_exp_f32_e32 v107, v107
	v_add_f32_e32 v104, 1.0, v104
	v_add_f32_e32 v105, 1.0, v105
	v_add_f32_e32 v106, 1.0, v106
	v_add_f32_e32 v107, 1.0, v107
	v_rcp_f32_e32 v104, v104
	v_rcp_f32_e32 v105, v105
	v_rcp_f32_e32 v106, v106
	v_rcp_f32_e32 v107, v107
	v_pk_add_f32 v[100:101], v[100:101], v[88:89]
	v_mul_f32_e32 v104, v80, v104
	v_mul_f32_e32 v105, v81, v105
	v_pk_add_f32 v[102:103], v[102:103], v[90:91]
	v_mul_f32_e32 v100, 0xbfb8aa3b, v100
	v_mul_f32_e32 v101, 0xbfb8aa3b, v101
	v_mul_f32_e32 v106, v82, v106
	v_mul_f32_e32 v107, v83, v107
	v_mul_f32_e32 v102, 0xbfb8aa3b, v102
	v_mul_f32_e32 v103, 0xbfb8aa3b, v103
	v_exp_f32_e32 v100, v100
	v_exp_f32_e32 v101, v101
	s_nop 0
	v_lshlrev_b32_e32 v123, 16, v194
	v_and_b32_e32 v120, 0xffff0000, v194
	v_lshlrev_b32_e32 v128, 16, v195
	v_and_b32_e32 v121, 0xffff0000, v195
	v_mul_f32_e32 v108, v108, v123
	v_mul_f32_e32 v109, v109, v120
	v_mul_f32_e32 v110, v110, v128
	v_mul_f32_e32 v111, v111, v121
	v_cvt_pk_bf16_f32 v108, v112, v108
	v_cvt_pk_bf16_f32 v109, v113, v109
	v_cvt_pk_bf16_f32 v110, v114, v110
	v_cvt_pk_bf16_f32 v111, v115, v111
	global_store_dwordx4 v[118:119], v[108:111], off
	s_nop 0
	v_lshlrev_b32_e32 v113, 9, v122
	v_ashrrev_i32_e32 v108, 31, v122
	v_alignbit_b32 v109, v108, v122, 11
	v_lshrrev_b32_e32 v114, 11, v108
	v_mad_u64_u32 v[108:109], s[30:31], v109, 12, s[6:7]
	v_mad_u32_u24 v109, v114, 12, v109
	v_and_b32_e32 v140, 0xffe00, v113
	v_exp_f32_e32 v113, v104
	v_exp_f32_e32 v114, v105
	v_exp_f32_e32 v115, v106
	v_exp_f32_e32 v120, v107
	v_exp_f32_e32 v102, v102
	v_exp_f32_e32 v103, v103
	v_fma_f32 v113, -v113, v113, 1.0
	v_fma_f32 v114, -v114, v114, 1.0
	v_add_f32_e32 v100, 1.0, v100
	v_add_f32_e32 v101, 1.0, v101
	v_fma_f32 v115, -v115, v115, 1.0
	v_fma_f32 v120, -v120, v120, 1.0
	v_max_f32_e32 v113, 0, v113
	v_max_f32_e32 v114, 0, v114
	v_add_f32_e32 v102, 1.0, v102
	v_add_f32_e32 v103, 1.0, v103
	v_rcp_f32_e32 v100, v100
	v_rcp_f32_e32 v101, v101
	v_max_f32_e32 v115, 0, v115
	v_max_f32_e32 v120, 0, v120
	v_sqrt_f32_e32 v113, v113
	v_sqrt_f32_e32 v114, v114
	v_rcp_f32_e32 v102, v102
	v_rcp_f32_e32 v103, v103
	v_sqrt_f32_e32 v115, v115
	v_sqrt_f32_e32 v120, v120
	v_lshlrev_b64 v[108:109], 20, v[108:109]
	v_lshl_add_u64 v[108:109], s[38:39], 0, v[108:109]
	v_lshl_add_u64 v[108:109], v[108:109], 0, v[140:141]
	v_mul_f32_e32 v100, v100, v113
	v_mul_f32_e32 v101, v101, v114
	v_lshl_add_u64 v[108:109], v[108:109], 0, s[44:45]
	v_mul_f32_e32 v102, v102, v115
	v_mul_f32_e32 v103, v103, v120
	v_add_u32_e32 v112, 0x90, v179
	v_lshl_add_u64 v[108:109], v[108:109], 0, v[150:151]
	v_pk_add_f32 v[92:93], v[92:93], v[96:97]
	v_pk_add_f32 v[94:95], v[94:95], v[98:99]
	v_mul_f32_e32 v92, 0xbfb8aa3b, v92
	v_exp_f32_e32 v92, v92
	v_mul_f32_e32 v93, 0xbfb8aa3b, v93
	v_exp_f32_e32 v93, v93
	v_mul_f32_e32 v94, 0xbfb8aa3b, v94
	v_add_f32_e32 v92, 1.0, v92
	v_mul_f32_e32 v95, 0xbfb8aa3b, v95
	v_exp_f32_e32 v94, v94
	v_rcp_f32_e32 v92, v92
	v_exp_f32_e32 v95, v95
	v_add_f32_e32 v93, 1.0, v93
	v_rcp_f32_e32 v93, v93
	v_pk_add_f32 v[84:85], v[84:85], v[88:89]
	v_add_f32_e32 v94, 1.0, v94
	v_mul_f32_e32 v92, v80, v92
	v_mul_f32_e32 v84, 0xbfb8aa3b, v84
	v_add_f32_e32 v95, 1.0, v95
	v_rcp_f32_e32 v94, v94
	v_exp_f32_e32 v84, v84
	v_rcp_f32_e32 v95, v95
	v_mul_f32_e32 v93, v81, v93
	v_mul_f32_e32 v85, 0xbfb8aa3b, v85
	v_exp_f32_e32 v85, v85
	v_pk_add_f32 v[86:87], v[86:87], v[90:91]
	v_mul_f32_e32 v94, v82, v94
	v_mul_f32_e32 v86, 0xbfb8aa3b, v86
	v_add_f32_e32 v84, 1.0, v84
	v_mul_f32_e32 v95, v83, v95
	v_mul_f32_e32 v87, 0xbfb8aa3b, v87
	v_exp_f32_e32 v86, v86
	v_rcp_f32_e32 v84, v84
	v_exp_f32_e32 v87, v87
	v_add_f32_e32 v85, 1.0, v85
	s_nop 0
	v_lshlrev_b32_e32 v113, 16, v196
	v_and_b32_e32 v110, 0xffff0000, v196
	v_lshlrev_b32_e32 v114, 16, v197
	v_and_b32_e32 v111, 0xffff0000, v197
	v_mul_f32_e32 v100, v100, v113
	v_mul_f32_e32 v101, v101, v110
	v_mul_f32_e32 v102, v102, v114
	v_mul_f32_e32 v103, v103, v111
	v_cvt_pk_bf16_f32 v100, v104, v100
	v_cvt_pk_bf16_f32 v101, v105, v101
	v_cvt_pk_bf16_f32 v102, v106, v102
	v_cvt_pk_bf16_f32 v103, v107, v103
	global_store_dwordx4 v[108:109], v[100:103], off
	v_ashrrev_i32_e32 v104, 31, v112
	v_alignbit_b32 v105, v104, v112, 11
	v_mad_i64_i32 v[100:101], s[30:31], v112, s96, v[164:165]
	v_lshl_add_u64 v[100:101], v[100:101], 0, v[166:167]
	s_nop 0
	v_lshrrev_b32_e32 v106, 11, v104
	v_mad_u64_u32 v[104:105], s[30:31], v105, 12, s[6:7]
	v_mad_u32_u24 v105, v106, 12, v105
	v_exp_f32_e32 v106, v92
	v_exp_f32_e32 v107, v93
	v_exp_f32_e32 v110, v94
	v_exp_f32_e32 v111, v95
	v_fma_f32 v106, -v106, v106, 1.0
	v_max_f32_e32 v106, 0, v106
	v_fma_f32 v107, -v107, v107, 1.0
	v_sqrt_f32_e32 v106, v106
	v_max_f32_e32 v107, 0, v107
	v_rcp_f32_e32 v85, v85
	v_sqrt_f32_e32 v107, v107
	v_fma_f32 v110, -v110, v110, 1.0
	v_add_f32_e32 v86, 1.0, v86
	v_fma_f32 v111, -v111, v111, 1.0
	v_max_f32_e32 v110, 0, v110
	v_mul_f32_e32 v84, v84, v106
	v_add_f32_e32 v87, 1.0, v87
	v_rcp_f32_e32 v86, v86
	v_max_f32_e32 v111, 0, v111
	v_sqrt_f32_e32 v110, v110
	v_lshlrev_b64 v[104:105], 20, v[104:105]
	v_rcp_f32_e32 v87, v87
	v_sqrt_f32_e32 v111, v111
	v_mul_f32_e32 v85, v85, v107
	v_lshl_add_u64 v[104:105], s[38:39], 0, v[104:105]
	v_mul_f32_e32 v86, v86, v110
	v_mul_f32_e32 v87, v87, v111
	v_pk_add_f32 v[76:77], v[76:77], v[96:97]
	v_pk_add_f32 v[78:79], v[78:79], v[98:99]
	v_mul_f32_e32 v76, 0xbfb8aa3b, v76
	v_mul_f32_e32 v77, 0xbfb8aa3b, v77
	v_mul_f32_e32 v78, 0xbfb8aa3b, v78
	v_exp_f32_e32 v76, v76
	v_exp_f32_e32 v77, v77
	v_exp_f32_e32 v78, v78
	v_mul_f32_e32 v79, 0xbfb8aa3b, v79
	v_add_f32_e32 v76, 1.0, v76
	v_add_f32_e32 v77, 1.0, v77
	v_add_f32_e32 v78, 1.0, v78
	v_rcp_f32_e32 v76, v76
	v_rcp_f32_e32 v77, v77
	v_rcp_f32_e32 v78, v78
	v_exp_f32_e32 v79, v79
	v_pk_add_f32 v[72:73], v[72:73], v[88:89]
	v_mul_f32_e32 v76, v80, v76
	v_pk_add_f32 v[74:75], v[74:75], v[90:91]
	v_mul_f32_e32 v72, 0xbfb8aa3b, v72
	v_mul_f32_e32 v77, v81, v77
	v_mul_f32_e32 v78, v82, v78
	v_mul_f32_e32 v73, 0xbfb8aa3b, v73
	v_mul_f32_e32 v74, 0xbfb8aa3b, v74
	v_exp_f32_e32 v72, v72
	v_exp_f32_e32 v73, v73
	v_exp_f32_e32 v74, v74
	v_add_f32_e32 v79, 1.0, v79
	v_rcp_f32_e32 v79, v79
	v_add_f32_e32 v72, 1.0, v72
	v_add_f32_e32 v73, 1.0, v73
	v_add_f32_e32 v74, 1.0, v74
	v_rcp_f32_e32 v72, v72
	v_rcp_f32_e32 v73, v73
	v_rcp_f32_e32 v74, v74
	v_mul_f32_e32 v79, v83, v79
	v_mul_f32_e32 v75, 0xbfb8aa3b, v75
	v_exp_f32_e32 v75, v75
	v_pk_add_f32 v[68:69], v[68:69], v[96:97]
	v_pk_add_f32 v[70:71], v[70:71], v[98:99]
	v_mul_f32_e32 v68, 0xbfb8aa3b, v68
	v_add_f32_e32 v75, 1.0, v75
	v_rcp_f32_e32 v75, v75
	v_exp_f32_e32 v68, v68
	v_mul_f32_e32 v69, 0xbfb8aa3b, v69
	v_mul_f32_e32 v70, 0xbfb8aa3b, v70
	v_mul_f32_e32 v71, 0xbfb8aa3b, v71
	v_add_f32_e32 v68, 1.0, v68
	s_nop 0
	v_lshlrev_b32_e32 v106, 16, v198
	v_mul_f32_e32 v84, v84, v106
	v_and_b32_e32 v102, 0xffff0000, v198
	v_cvt_pk_bf16_f32 v92, v92, v84
	v_lshlrev_b32_e32 v84, 9, v112
	v_mul_f32_e32 v85, v85, v102
	v_and_b32_e32 v140, 0xffe00, v84
	v_cvt_pk_bf16_f32 v93, v93, v85
	v_lshl_add_u64 v[84:85], v[104:105], 0, v[140:141]
	v_lshlrev_b32_e32 v107, 16, v199
	v_lshl_add_u64 v[84:85], v[84:85], 0, s[44:45]
	v_and_b32_e32 v103, 0xffff0000, v199
	v_mul_f32_e32 v86, v86, v107
	v_cvt_pk_bf16_f32 v94, v94, v86
	v_lshl_add_u64 v[84:85], v[84:85], 0, v[150:151]
	v_mul_f32_e32 v87, v87, v103
	v_cvt_pk_bf16_f32 v95, v95, v87
	global_store_dwordx4 v[84:85], v[92:95], off
	v_exp_f32_e32 v102, v76
	v_exp_f32_e32 v103, v77
	v_add_u32_e32 v94, 0xa0, v179
	v_mad_i64_i32 v[86:87], s[30:31], v94, s96, v[164:165]
	v_lshl_add_u64 v[86:87], v[86:87], 0, v[166:167]
	s_nop 0
	v_exp_f32_e32 v104, v78
	v_fma_f32 v102, -v102, v102, 1.0
	v_fma_f32 v103, -v103, v103, 1.0
	v_max_f32_e32 v102, 0, v102
	v_fma_f32 v104, -v104, v104, 1.0
	v_max_f32_e32 v103, 0, v103
	v_max_f32_e32 v104, 0, v104
	v_sqrt_f32_e32 v102, v102
	v_sqrt_f32_e32 v103, v103
	v_sqrt_f32_e32 v104, v104
	v_exp_f32_e32 v105, v79
	v_mul_f32_e32 v72, v72, v102
	v_ashrrev_i32_e32 v95, 31, v94
	v_mul_f32_e32 v73, v73, v103
	v_mul_f32_e32 v74, v74, v104
	v_fma_f32 v105, -v105, v105, 1.0
	v_max_f32_e32 v105, 0, v105
	v_sqrt_f32_e32 v105, v105
	v_exp_f32_e32 v69, v69
	v_exp_f32_e32 v70, v70
	v_rcp_f32_e32 v68, v68
	v_mul_f32_e32 v75, v75, v105
	v_exp_f32_e32 v71, v71
	v_pk_add_f32 v[64:65], v[64:65], v[88:89]
	v_add_f32_e32 v69, 1.0, v69
	v_add_f32_e32 v70, 1.0, v70
	v_mul_f32_e32 v68, v80, v68
	v_mul_f32_e32 v64, 0xbfb8aa3b, v64
	v_add_f32_e32 v71, 1.0, v71
	v_rcp_f32_e32 v69, v69
	v_rcp_f32_e32 v70, v70
	v_exp_f32_e32 v80, v68
	v_exp_f32_e32 v64, v64
	v_rcp_f32_e32 v71, v71
	v_pk_add_f32 v[66:67], v[66:67], v[90:91]
	v_mul_f32_e32 v69, v81, v69
	v_mul_f32_e32 v70, v82, v70
	v_fma_f32 v80, -v80, v80, 1.0
	v_mul_f32_e32 v65, 0xbfb8aa3b, v65
	v_mul_f32_e32 v66, 0xbfb8aa3b, v66
	v_add_f32_e32 v64, 1.0, v64
	v_mul_f32_e32 v71, v83, v71
	v_exp_f32_e32 v81, v69
	v_exp_f32_e32 v82, v70
	v_max_f32_e32 v80, 0, v80
	v_mul_f32_e32 v67, 0xbfb8aa3b, v67
	v_exp_f32_e32 v65, v65
	v_exp_f32_e32 v66, v66
	v_rcp_f32_e32 v64, v64
	v_exp_f32_e32 v83, v71
	v_sqrt_f32_e32 v80, v80
	v_exp_f32_e32 v67, v67
	v_fma_f32 v81, -v81, v81, 1.0
	v_fma_f32 v82, -v82, v82, 1.0
	v_add_f32_e32 v65, 1.0, v65
	v_add_f32_e32 v66, 1.0, v66
	v_fma_f32 v83, -v83, v83, 1.0
	v_max_f32_e32 v81, 0, v81
	v_max_f32_e32 v82, 0, v82
	v_mul_f32_e32 v64, v64, v80
	v_add_f32_e32 v67, 1.0, v67
	v_rcp_f32_e32 v65, v65
	v_rcp_f32_e32 v66, v66
	v_sqrt_f32_e32 v81, v81
	v_max_f32_e32 v83, 0, v83
	v_sqrt_f32_e32 v82, v82
	v_rcp_f32_e32 v67, v67
	v_mul_f32_e32 v65, v65, v81
	v_mul_f32_e32 v66, v66, v82
	s_nop 0
	v_lshlrev_b32_e32 v102, 16, v200
	v_and_b32_e32 v92, 0xffff0000, v200
	v_lshlrev_b32_e32 v103, 16, v201
	v_mul_f32_e32 v72, v72, v102
	v_mul_f32_e32 v73, v73, v92
	v_mul_f32_e32 v74, v74, v103
	v_cvt_pk_bf16_f32 v72, v76, v72
	v_alignbit_b32 v76, v95, v94, 11
	v_cvt_pk_bf16_f32 v73, v77, v73
	v_cvt_pk_bf16_f32 v74, v78, v74
	v_mad_u64_u32 v[76:77], s[30:31], v76, 12, s[6:7]
	v_lshrrev_b32_e32 v78, 11, v95
	v_mad_u32_u24 v77, v78, 12, v77
	v_lshlrev_b64 v[76:77], 20, v[76:77]
	v_lshlrev_b32_e32 v78, 9, v94
	v_lshl_add_u64 v[76:77], s[38:39], 0, v[76:77]
	v_and_b32_e32 v140, 0xffe00, v78
	v_lshl_add_u64 v[76:77], v[76:77], 0, v[140:141]
	v_and_b32_e32 v93, 0xffff0000, v201
	v_lshl_add_u64 v[76:77], v[76:77], 0, s[44:45]
	v_mul_f32_e32 v75, v75, v93
	v_lshl_add_u64 v[76:77], v[76:77], 0, v[150:151]
	v_cvt_pk_bf16_f32 v75, v79, v75
	global_store_dwordx4 v[76:77], v[72:75], off
	s_nop 1
	v_add_u32_e32 v74, 0xb0, v179
	v_mad_i64_i32 v[72:73], s[30:31], v74, s96, v[164:165]
	v_lshl_add_u64 v[78:79], v[72:73], 0, v[166:167]
	s_nop 0
	v_ashrrev_i32_e32 v75, 31, v74
	s_nop 0
	v_lshlrev_b32_e32 v80, 16, v202
	v_mul_f32_e32 v64, v64, v80
	v_cvt_pk_bf16_f32 v64, v68, v64
	v_sqrt_f32_e32 v68, v83
	v_and_b32_e32 v72, 0xffff0000, v202
	v_lshlrev_b32_e32 v81, 16, v203
	v_mul_f32_e32 v65, v65, v72
	v_mul_f32_e32 v66, v66, v81
	v_mul_f32_e32 v67, v67, v68
	v_alignbit_b32 v68, v75, v74, 11
	v_cvt_pk_bf16_f32 v65, v69, v65
	v_cvt_pk_bf16_f32 v66, v70, v66
	v_mad_u64_u32 v[68:69], s[30:31], v68, 12, s[6:7]
	v_lshrrev_b32_e32 v70, 11, v75
	v_mad_u32_u24 v69, v70, 12, v69
	v_lshlrev_b64 v[68:69], 20, v[68:69]
	v_lshlrev_b32_e32 v70, 9, v74
	v_lshl_add_u64 v[68:69], s[38:39], 0, v[68:69]
	v_and_b32_e32 v140, 0xffe00, v70
	v_lshl_add_u64 v[68:69], v[68:69], 0, v[140:141]
	v_and_b32_e32 v73, 0xffff0000, v203
	v_lshl_add_u64 v[68:69], v[68:69], 0, s[44:45]
	v_mul_f32_e32 v67, v67, v73
	v_lshl_add_u64 v[80:81], v[68:69], 0, v[150:151]
	v_cvt_pk_bf16_f32 v67, v71, v67
	global_store_dwordx4 v[80:81], v[64:67], off
	global_load_dwordx4 v[72:75], v[156:157], off offset:16
	global_load_dwordx4 v[68:71], v[158:159], off offset:16
	global_load_dwordx2 v[82:83], v[160:161], off offset:8
	s_nop 0
	global_load_dwordx4 v[64:67], v[162:163], off offset:16
	s_waitcnt vmcnt(3)
	v_pk_add_f32 v[62:63], v[62:63], v[74:75]
	v_pk_add_f32 v[60:61], v[60:61], v[72:73]
	v_mul_f32_e32 v62, 0xbfb8aa3b, v62
	v_mul_f32_e32 v60, 0xbfb8aa3b, v60
	v_mul_f32_e32 v61, 0xbfb8aa3b, v61
	v_mul_f32_e32 v63, 0xbfb8aa3b, v63
	v_exp_f32_e32 v60, v60
	v_exp_f32_e32 v61, v61
	v_exp_f32_e32 v62, v62
	v_exp_f32_e32 v63, v63
	v_add_f32_e32 v60, 1.0, v60
	v_add_f32_e32 v61, 1.0, v61
	v_add_f32_e32 v62, 1.0, v62
	v_add_f32_e32 v63, 1.0, v63
	v_rcp_f32_e32 v60, v60
	v_rcp_f32_e32 v61, v61
	v_rcp_f32_e32 v62, v62
	v_rcp_f32_e32 v63, v63
	s_waitcnt vmcnt(2)
	v_pk_add_f32 v[58:59], v[58:59], v[70:71]
	v_pk_add_f32 v[56:57], v[56:57], v[68:69]
	s_waitcnt vmcnt(0)
	v_mul_f32_e32 v60, v64, v60
	v_mul_f32_e32 v61, v65, v61
	v_mul_f32_e32 v62, v66, v62
	v_mul_f32_e32 v63, v67, v63
	v_mul_f32_e32 v56, 0xbfb8aa3b, v56
	v_mul_f32_e32 v57, 0xbfb8aa3b, v57
	v_mul_f32_e32 v58, 0xbfb8aa3b, v58
	v_mul_f32_e32 v59, 0xbfb8aa3b, v59
	v_exp_f32_e32 v90, v60
	v_exp_f32_e32 v91, v61
	v_exp_f32_e32 v92, v62
	v_exp_f32_e32 v93, v63
	v_exp_f32_e32 v56, v56
	v_exp_f32_e32 v57, v57
	v_exp_f32_e32 v58, v58
	v_exp_f32_e32 v59, v59
	v_fma_f32 v90, -v90, v90, 1.0
	v_fma_f32 v91, -v91, v91, 1.0
	v_fma_f32 v92, -v92, v92, 1.0
	v_fma_f32 v93, -v93, v93, 1.0
	v_add_f32_e32 v56, 1.0, v56
	v_add_f32_e32 v57, 1.0, v57
	v_add_f32_e32 v58, 1.0, v58
	v_add_f32_e32 v59, 1.0, v59
	v_max_f32_e32 v90, 0, v90
	v_max_f32_e32 v91, 0, v91
	v_max_f32_e32 v92, 0, v92
	v_max_f32_e32 v93, 0, v93
	v_rcp_f32_e32 v56, v56
	v_rcp_f32_e32 v57, v57
	v_rcp_f32_e32 v58, v58
	v_rcp_f32_e32 v59, v59
	v_sqrt_f32_e32 v90, v90
	v_sqrt_f32_e32 v91, v91
	v_sqrt_f32_e32 v92, v92
	v_sqrt_f32_e32 v93, v93
	v_lshlrev_b32_e32 v88, 16, v82
	v_and_b32_e32 v82, 0xffff0000, v82
	v_lshlrev_b32_e32 v89, 16, v83
	v_and_b32_e32 v83, 0xffff0000, v83
	v_mul_f32_e32 v56, v56, v90
	v_mul_f32_e32 v57, v57, v91
	v_mul_f32_e32 v58, v58, v92
	v_mul_f32_e32 v59, v59, v93
	v_mul_f32_e32 v56, v56, v88
	v_mul_f32_e32 v57, v57, v82
	v_mul_f32_e32 v58, v58, v89
	v_mul_f32_e32 v59, v59, v83
	v_cvt_pk_bf16_f32 v56, v60, v56
	v_cvt_pk_bf16_f32 v57, v61, v57
	v_cvt_pk_bf16_f32 v58, v62, v58
	v_cvt_pk_bf16_f32 v59, v63, v59
	global_store_dwordx4 v[154:155], v[56:59], off offset:16
	s_nop 0
	v_pk_add_f32 v[54:55], v[54:55], v[74:75]
	v_pk_add_f32 v[52:53], v[52:53], v[72:73]
	v_mul_f32_e32 v54, 0xbfb8aa3b, v54
	v_mul_f32_e32 v52, 0xbfb8aa3b, v52
	v_mul_f32_e32 v53, 0xbfb8aa3b, v53
	v_mul_f32_e32 v55, 0xbfb8aa3b, v55
	v_exp_f32_e32 v52, v52
	v_exp_f32_e32 v53, v53
	v_exp_f32_e32 v54, v54
	v_exp_f32_e32 v55, v55
	v_add_f32_e32 v52, 1.0, v52
	v_add_f32_e32 v53, 1.0, v53
	v_add_f32_e32 v54, 1.0, v54
	v_add_f32_e32 v55, 1.0, v55
	v_rcp_f32_e32 v52, v52
	v_rcp_f32_e32 v53, v53
	v_rcp_f32_e32 v54, v54
	v_rcp_f32_e32 v55, v55
	v_pk_add_f32 v[50:51], v[50:51], v[70:71]
	v_pk_add_f32 v[48:49], v[48:49], v[68:69]
	v_mul_f32_e32 v52, v64, v52
	v_mul_f32_e32 v53, v65, v53
	v_mul_f32_e32 v54, v66, v54
	v_mul_f32_e32 v55, v67, v55
	v_mul_f32_e32 v48, 0xbfb8aa3b, v48
	v_mul_f32_e32 v49, 0xbfb8aa3b, v49
	v_mul_f32_e32 v50, 0xbfb8aa3b, v50
	v_mul_f32_e32 v51, 0xbfb8aa3b, v51
	v_exp_f32_e32 v58, v52
	v_exp_f32_e32 v59, v53
	v_exp_f32_e32 v60, v54
	v_exp_f32_e32 v61, v55
	v_exp_f32_e32 v48, v48
	v_exp_f32_e32 v49, v49
	v_exp_f32_e32 v50, v50
	v_exp_f32_e32 v51, v51
	v_fma_f32 v58, -v58, v58, 1.0
	v_fma_f32 v59, -v59, v59, 1.0
	v_fma_f32 v60, -v60, v60, 1.0
	v_fma_f32 v61, -v61, v61, 1.0
	v_add_f32_e32 v48, 1.0, v48
	v_add_f32_e32 v49, 1.0, v49
	v_add_f32_e32 v50, 1.0, v50
	v_add_f32_e32 v51, 1.0, v51
	v_max_f32_e32 v58, 0, v58
	v_max_f32_e32 v59, 0, v59
	v_max_f32_e32 v60, 0, v60
	v_max_f32_e32 v61, 0, v61
	v_rcp_f32_e32 v48, v48
	v_rcp_f32_e32 v49, v49
	v_rcp_f32_e32 v50, v50
	v_rcp_f32_e32 v51, v51
	v_sqrt_f32_e32 v58, v58
	v_sqrt_f32_e32 v59, v59
	v_sqrt_f32_e32 v60, v60
	v_sqrt_f32_e32 v61, v61
	v_mul_f32_e32 v48, v48, v58
	v_mul_f32_e32 v49, v49, v59
	v_mul_f32_e32 v50, v50, v60
	v_mul_f32_e32 v51, v51, v61
	v_pk_add_f32 v[46:47], v[46:47], v[74:75]
	v_pk_add_f32 v[44:45], v[44:45], v[72:73]
	v_mul_f32_e32 v46, 0xbfb8aa3b, v46
	v_mul_f32_e32 v44, 0xbfb8aa3b, v44
	v_mul_f32_e32 v45, 0xbfb8aa3b, v45
	v_mul_f32_e32 v47, 0xbfb8aa3b, v47
	v_exp_f32_e32 v44, v44
	v_exp_f32_e32 v45, v45
	v_exp_f32_e32 v46, v46
	v_exp_f32_e32 v47, v47
	v_add_f32_e32 v44, 1.0, v44
	v_add_f32_e32 v45, 1.0, v45
	v_add_f32_e32 v46, 1.0, v46
	v_add_f32_e32 v47, 1.0, v47
	v_rcp_f32_e32 v44, v44
	v_rcp_f32_e32 v45, v45
	v_rcp_f32_e32 v46, v46
	v_rcp_f32_e32 v47, v47
	v_pk_add_f32 v[42:43], v[42:43], v[70:71]
	s_nop 0
	v_lshlrev_b32_e32 v58, 16, v204
	v_and_b32_e32 v56, 0xffff0000, v204
	v_lshlrev_b32_e32 v59, 16, v205
	v_and_b32_e32 v57, 0xffff0000, v205
	v_mul_f32_e32 v48, v48, v58
	v_mul_f32_e32 v49, v49, v56
	v_mul_f32_e32 v50, v50, v59
	v_mul_f32_e32 v51, v51, v57
	v_cvt_pk_bf16_f32 v48, v52, v48
	v_cvt_pk_bf16_f32 v49, v53, v49
	v_cvt_pk_bf16_f32 v50, v54, v50
	v_cvt_pk_bf16_f32 v51, v55, v51
	global_store_dwordx4 v[134:135], v[48:51], off offset:16
	s_nop 0
	v_pk_add_f32 v[40:41], v[40:41], v[68:69]
	v_mul_f32_e32 v44, v64, v44
	v_mul_f32_e32 v45, v65, v45
	v_mul_f32_e32 v46, v66, v46
	v_mul_f32_e32 v47, v67, v47
	v_mul_f32_e32 v40, 0xbfb8aa3b, v40
	v_mul_f32_e32 v41, 0xbfb8aa3b, v41
	v_mul_f32_e32 v42, 0xbfb8aa3b, v42
	v_mul_f32_e32 v43, 0xbfb8aa3b, v43
	v_exp_f32_e32 v50, v44
	v_exp_f32_e32 v51, v45
	v_exp_f32_e32 v52, v46
	v_exp_f32_e32 v53, v47
	v_exp_f32_e32 v40, v40
	v_exp_f32_e32 v41, v41
	v_exp_f32_e32 v42, v42
	v_exp_f32_e32 v43, v43
	v_fma_f32 v50, -v50, v50, 1.0
	v_fma_f32 v51, -v51, v51, 1.0
	v_fma_f32 v52, -v52, v52, 1.0
	v_fma_f32 v53, -v53, v53, 1.0
	v_add_f32_e32 v40, 1.0, v40
	v_add_f32_e32 v41, 1.0, v41
	v_add_f32_e32 v42, 1.0, v42
	v_add_f32_e32 v43, 1.0, v43
	v_max_f32_e32 v50, 0, v50
	v_max_f32_e32 v51, 0, v51
	v_max_f32_e32 v52, 0, v52
	v_max_f32_e32 v53, 0, v53
	v_rcp_f32_e32 v40, v40
	v_rcp_f32_e32 v41, v41
	v_rcp_f32_e32 v42, v42
	v_rcp_f32_e32 v43, v43
	v_sqrt_f32_e32 v50, v50
	v_sqrt_f32_e32 v51, v51
	v_sqrt_f32_e32 v52, v52
	v_sqrt_f32_e32 v53, v53
	v_mul_f32_e32 v40, v40, v50
	v_mul_f32_e32 v41, v41, v51
	v_mul_f32_e32 v42, v42, v52
	v_mul_f32_e32 v43, v43, v53
	v_pk_add_f32 v[38:39], v[38:39], v[74:75]
	v_pk_add_f32 v[36:37], v[36:37], v[72:73]
	v_mul_f32_e32 v38, 0xbfb8aa3b, v38
	v_mul_f32_e32 v36, 0xbfb8aa3b, v36
	v_mul_f32_e32 v37, 0xbfb8aa3b, v37
	v_mul_f32_e32 v39, 0xbfb8aa3b, v39
	v_exp_f32_e32 v36, v36
	v_exp_f32_e32 v37, v37
	v_exp_f32_e32 v38, v38
	v_exp_f32_e32 v39, v39
	v_add_f32_e32 v36, 1.0, v36
	v_add_f32_e32 v37, 1.0, v37
	v_add_f32_e32 v38, 1.0, v38
	v_add_f32_e32 v39, 1.0, v39
	v_rcp_f32_e32 v36, v36
	v_rcp_f32_e32 v37, v37
	v_rcp_f32_e32 v38, v38
	v_rcp_f32_e32 v39, v39
	v_pk_add_f32 v[34:35], v[34:35], v[70:71]
	v_pk_add_f32 v[32:33], v[32:33], v[68:69]
	v_mul_f32_e32 v36, v64, v36
	v_mul_f32_e32 v37, v65, v37
	v_mul_f32_e32 v38, v66, v38
	v_mul_f32_e32 v39, v67, v39
	v_mul_f32_e32 v32, 0xbfb8aa3b, v32
	v_mul_f32_e32 v33, 0xbfb8aa3b, v33
	v_mul_f32_e32 v34, 0xbfb8aa3b, v34
	v_mul_f32_e32 v35, 0xbfb8aa3b, v35
	v_exp_f32_e32 v32, v32
	v_exp_f32_e32 v33, v33
	v_exp_f32_e32 v34, v34
	v_exp_f32_e32 v35, v35
	v_add_f32_e32 v32, 1.0, v32
	v_add_f32_e32 v33, 1.0, v33
	v_add_f32_e32 v34, 1.0, v34
	v_add_f32_e32 v35, 1.0, v35
	v_rcp_f32_e32 v32, v32
	v_rcp_f32_e32 v33, v33
	s_nop 0
	v_lshlrev_b32_e32 v50, 16, v206
	v_and_b32_e32 v48, 0xffff0000, v206
	v_lshlrev_b32_e32 v51, 16, v207
	v_and_b32_e32 v49, 0xffff0000, v207
	v_mul_f32_e32 v40, v40, v50
	v_mul_f32_e32 v41, v41, v48
	v_mul_f32_e32 v42, v42, v51
	v_mul_f32_e32 v43, v43, v49
	v_cvt_pk_bf16_f32 v40, v44, v40
	v_cvt_pk_bf16_f32 v41, v45, v41
	v_cvt_pk_bf16_f32 v42, v46, v42
	v_cvt_pk_bf16_f32 v43, v47, v43
	global_store_dwordx4 v[126:127], v[40:43], off offset:16
	s_nop 0
	v_exp_f32_e32 v44, v38
	v_exp_f32_e32 v42, v36
	v_exp_f32_e32 v43, v37
	v_exp_f32_e32 v45, v39
	v_fma_f32 v44, -v44, v44, 1.0
	v_fma_f32 v42, -v42, v42, 1.0
	v_fma_f32 v43, -v43, v43, 1.0
	v_fma_f32 v45, -v45, v45, 1.0
	v_max_f32_e32 v42, 0, v42
	v_max_f32_e32 v43, 0, v43
	v_max_f32_e32 v44, 0, v44
	v_max_f32_e32 v45, 0, v45
	v_rcp_f32_e32 v34, v34
	v_rcp_f32_e32 v35, v35
	v_sqrt_f32_e32 v42, v42
	v_sqrt_f32_e32 v43, v43
	v_sqrt_f32_e32 v44, v44
	v_sqrt_f32_e32 v45, v45
	v_mul_f32_e32 v32, v32, v42
	v_mul_f32_e32 v33, v33, v43
	v_mul_f32_e32 v34, v34, v44
	v_mul_f32_e32 v35, v35, v45
	v_pk_add_f32 v[30:31], v[30:31], v[74:75]
	v_pk_add_f32 v[28:29], v[28:29], v[72:73]
	v_mul_f32_e32 v30, 0xbfb8aa3b, v30
	v_mul_f32_e32 v28, 0xbfb8aa3b, v28
	v_mul_f32_e32 v29, 0xbfb8aa3b, v29
	v_mul_f32_e32 v31, 0xbfb8aa3b, v31
	v_exp_f32_e32 v28, v28
	v_exp_f32_e32 v29, v29
	v_exp_f32_e32 v30, v30
	v_exp_f32_e32 v31, v31
	v_add_f32_e32 v28, 1.0, v28
	v_add_f32_e32 v29, 1.0, v29
	v_add_f32_e32 v30, 1.0, v30
	v_add_f32_e32 v31, 1.0, v31
	v_rcp_f32_e32 v28, v28
	v_rcp_f32_e32 v29, v29
	v_rcp_f32_e32 v30, v30
	v_rcp_f32_e32 v31, v31
	v_pk_add_f32 v[26:27], v[26:27], v[70:71]
	v_pk_add_f32 v[24:25], v[24:25], v[68:69]
	v_mul_f32_e32 v28, v64, v28
	v_mul_f32_e32 v29, v65, v29
	v_mul_f32_e32 v30, v66, v30
	v_mul_f32_e32 v31, v67, v31
	v_mul_f32_e32 v24, 0xbfb8aa3b, v24
	v_mul_f32_e32 v25, 0xbfb8aa3b, v25
	v_mul_f32_e32 v26, 0xbfb8aa3b, v26
	v_mul_f32_e32 v27, 0xbfb8aa3b, v27
	v_exp_f32_e32 v24, v24
	v_exp_f32_e32 v25, v25
	v_exp_f32_e32 v26, v26
	v_exp_f32_e32 v27, v27
	v_add_f32_e32 v24, 1.0, v24
	v_add_f32_e32 v25, 1.0, v25
	v_add_f32_e32 v26, 1.0, v26
	v_add_f32_e32 v27, 1.0, v27
	v_rcp_f32_e32 v24, v24
	v_rcp_f32_e32 v25, v25
	v_rcp_f32_e32 v26, v26
	v_rcp_f32_e32 v27, v27
	v_pk_add_f32 v[22:23], v[22:23], v[74:75]
	v_pk_add_f32 v[20:21], v[20:21], v[72:73]
	v_mul_f32_e32 v22, 0xbfb8aa3b, v22
	v_mul_f32_e32 v20, 0xbfb8aa3b, v20
	v_mul_f32_e32 v21, 0xbfb8aa3b, v21
	v_mul_f32_e32 v23, 0xbfb8aa3b, v23
	v_exp_f32_e32 v20, v20
	v_exp_f32_e32 v21, v21
	v_exp_f32_e32 v22, v22
	v_exp_f32_e32 v23, v23
	v_add_f32_e32 v20, 1.0, v20
	v_add_f32_e32 v21, 1.0, v21
	v_add_f32_e32 v22, 1.0, v22
	v_add_f32_e32 v23, 1.0, v23
	v_rcp_f32_e32 v20, v20
	v_rcp_f32_e32 v21, v21
	v_rcp_f32_e32 v22, v22
	s_nop 0
	v_lshlrev_b32_e32 v42, 16, v208
	v_and_b32_e32 v40, 0xffff0000, v208
	v_lshlrev_b32_e32 v43, 16, v209
	v_and_b32_e32 v41, 0xffff0000, v209
	v_mul_f32_e32 v32, v32, v42
	v_mul_f32_e32 v33, v33, v40
	v_mul_f32_e32 v34, v34, v43
	v_mul_f32_e32 v35, v35, v41
	v_cvt_pk_bf16_f32 v32, v36, v32
	v_cvt_pk_bf16_f32 v33, v37, v33
	v_cvt_pk_bf16_f32 v34, v38, v34
	v_cvt_pk_bf16_f32 v35, v39, v35
	global_store_dwordx4 v[118:119], v[32:35], off offset:16
	s_nop 0
	v_exp_f32_e32 v36, v30
	v_exp_f32_e32 v34, v28
	v_exp_f32_e32 v35, v29
	v_exp_f32_e32 v37, v31
	v_fma_f32 v36, -v36, v36, 1.0
	v_fma_f32 v34, -v34, v34, 1.0
	v_fma_f32 v35, -v35, v35, 1.0
	v_fma_f32 v37, -v37, v37, 1.0
	v_max_f32_e32 v34, 0, v34
	v_max_f32_e32 v35, 0, v35
	v_max_f32_e32 v36, 0, v36
	v_max_f32_e32 v37, 0, v37
	v_sqrt_f32_e32 v34, v34
	v_sqrt_f32_e32 v35, v35
	v_sqrt_f32_e32 v36, v36
	v_sqrt_f32_e32 v37, v37
	v_mul_f32_e32 v24, v24, v34
	v_mul_f32_e32 v25, v25, v35
	v_mul_f32_e32 v26, v26, v36
	v_mul_f32_e32 v27, v27, v37
	v_rcp_f32_e32 v23, v23
	v_pk_add_f32 v[18:19], v[18:19], v[70:71]
	v_pk_add_f32 v[16:17], v[16:17], v[68:69]
	v_mul_f32_e32 v20, v64, v20
	v_mul_f32_e32 v21, v65, v21
	v_mul_f32_e32 v22, v66, v22
	v_mul_f32_e32 v23, v67, v23
	v_mul_f32_e32 v16, 0xbfb8aa3b, v16
	v_mul_f32_e32 v17, 0xbfb8aa3b, v17
	v_mul_f32_e32 v18, 0xbfb8aa3b, v18
	v_mul_f32_e32 v19, 0xbfb8aa3b, v19
	v_exp_f32_e32 v16, v16
	v_exp_f32_e32 v17, v17
	v_exp_f32_e32 v18, v18
	v_exp_f32_e32 v19, v19
	v_add_f32_e32 v16, 1.0, v16
	v_add_f32_e32 v17, 1.0, v17
	v_add_f32_e32 v18, 1.0, v18
	v_add_f32_e32 v19, 1.0, v19
	v_rcp_f32_e32 v16, v16
	v_rcp_f32_e32 v17, v17
	v_rcp_f32_e32 v18, v18
	v_rcp_f32_e32 v19, v19
	v_pk_add_f32 v[14:15], v[14:15], v[74:75]
	v_pk_add_f32 v[12:13], v[12:13], v[72:73]
	v_mul_f32_e32 v14, 0xbfb8aa3b, v14
	v_mul_f32_e32 v12, 0xbfb8aa3b, v12
	v_mul_f32_e32 v13, 0xbfb8aa3b, v13
	v_mul_f32_e32 v15, 0xbfb8aa3b, v15
	v_exp_f32_e32 v12, v12
	v_exp_f32_e32 v13, v13
	v_exp_f32_e32 v14, v14
	v_exp_f32_e32 v15, v15
	v_add_f32_e32 v12, 1.0, v12
	v_add_f32_e32 v13, 1.0, v13
	v_add_f32_e32 v14, 1.0, v14
	v_add_f32_e32 v15, 1.0, v15
	v_rcp_f32_e32 v12, v12
	v_rcp_f32_e32 v13, v13
	v_rcp_f32_e32 v14, v14
	v_rcp_f32_e32 v15, v15
	v_pk_add_f32 v[10:11], v[10:11], v[70:71]
	v_pk_add_f32 v[8:9], v[8:9], v[68:69]
	v_mul_f32_e32 v12, v64, v12
	v_mul_f32_e32 v13, v65, v13
	v_mul_f32_e32 v14, v66, v14
	v_mul_f32_e32 v15, v67, v15
	v_mul_f32_e32 v8, 0xbfb8aa3b, v8
	v_mul_f32_e32 v9, 0xbfb8aa3b, v9
	v_mul_f32_e32 v10, 0xbfb8aa3b, v10
	v_mul_f32_e32 v11, 0xbfb8aa3b, v11
	v_exp_f32_e32 v8, v8
	v_exp_f32_e32 v9, v9
	v_exp_f32_e32 v10, v10
	v_exp_f32_e32 v11, v11
	v_add_f32_e32 v8, 1.0, v8
	v_add_f32_e32 v9, 1.0, v9
	v_add_f32_e32 v10, 1.0, v10
	v_add_f32_e32 v11, 1.0, v11
	s_nop 0
	v_lshlrev_b32_e32 v34, 16, v210
	v_and_b32_e32 v32, 0xffff0000, v210
	v_lshlrev_b32_e32 v35, 16, v211
	v_and_b32_e32 v33, 0xffff0000, v211
	v_mul_f32_e32 v24, v24, v34
	v_mul_f32_e32 v25, v25, v32
	v_mul_f32_e32 v26, v26, v35
	v_mul_f32_e32 v27, v27, v33
	v_cvt_pk_bf16_f32 v24, v28, v24
	v_cvt_pk_bf16_f32 v25, v29, v25
	v_cvt_pk_bf16_f32 v26, v30, v26
	v_cvt_pk_bf16_f32 v27, v31, v27
	global_store_dwordx4 v[108:109], v[24:27], off offset:16
	s_nop 0
	v_exp_f32_e32 v28, v22
	v_exp_f32_e32 v26, v20
	v_exp_f32_e32 v27, v21
	v_exp_f32_e32 v29, v23
	v_fma_f32 v28, -v28, v28, 1.0
	v_fma_f32 v26, -v26, v26, 1.0
	v_fma_f32 v27, -v27, v27, 1.0
	v_fma_f32 v29, -v29, v29, 1.0
	v_max_f32_e32 v26, 0, v26
	v_max_f32_e32 v27, 0, v27
	v_max_f32_e32 v28, 0, v28
	v_max_f32_e32 v29, 0, v29
	v_sqrt_f32_e32 v26, v26
	v_sqrt_f32_e32 v27, v27
	v_sqrt_f32_e32 v28, v28
	v_sqrt_f32_e32 v29, v29
	v_mul_f32_e32 v16, v16, v26
	v_mul_f32_e32 v17, v17, v27
	v_mul_f32_e32 v18, v18, v28
	v_mul_f32_e32 v19, v19, v29
	v_rcp_f32_e32 v8, v8
	v_rcp_f32_e32 v9, v9
	v_rcp_f32_e32 v10, v10
	v_rcp_f32_e32 v11, v11
	v_pk_add_f32 v[6:7], v[6:7], v[74:75]
	v_pk_add_f32 v[4:5], v[4:5], v[72:73]
	v_mul_f32_e32 v6, 0xbfb8aa3b, v6
	v_mul_f32_e32 v4, 0xbfb8aa3b, v4
	v_mul_f32_e32 v5, 0xbfb8aa3b, v5
	v_mul_f32_e32 v7, 0xbfb8aa3b, v7
	v_exp_f32_e32 v4, v4
	v_exp_f32_e32 v5, v5
	v_exp_f32_e32 v6, v6
	v_exp_f32_e32 v7, v7
	v_add_f32_e32 v4, 1.0, v4
	v_add_f32_e32 v5, 1.0, v5
	v_add_f32_e32 v6, 1.0, v6
	v_add_f32_e32 v7, 1.0, v7
	v_rcp_f32_e32 v4, v4
	v_rcp_f32_e32 v5, v5
	v_rcp_f32_e32 v6, v6
	v_rcp_f32_e32 v7, v7
	v_pk_add_f32 v[2:3], v[2:3], v[70:71]
	v_pk_add_f32 v[0:1], v[0:1], v[68:69]
	v_mul_f32_e32 v4, v64, v4
	v_mul_f32_e32 v5, v65, v5
	v_mul_f32_e32 v6, v66, v6
	v_mul_f32_e32 v7, v67, v7
	v_mul_f32_e32 v0, 0xbfb8aa3b, v0
	v_mul_f32_e32 v1, 0xbfb8aa3b, v1
	v_mul_f32_e32 v2, 0xbfb8aa3b, v2
	v_mul_f32_e32 v3, 0xbfb8aa3b, v3
	v_exp_f32_e32 v0, v0
	v_exp_f32_e32 v1, v1
	v_exp_f32_e32 v2, v2
	v_exp_f32_e32 v3, v3
	v_add_f32_e32 v0, 1.0, v0
	v_add_f32_e32 v1, 1.0, v1
	v_add_f32_e32 v2, 1.0, v2
	v_add_f32_e32 v3, 1.0, v3
	v_rcp_f32_e32 v0, v0
	v_rcp_f32_e32 v1, v1
	v_rcp_f32_e32 v2, v2
	v_rcp_f32_e32 v3, v3
	s_nop 0
	v_lshlrev_b32_e32 v26, 16, v212
	v_and_b32_e32 v24, 0xffff0000, v212
	v_lshlrev_b32_e32 v27, 16, v213
	v_and_b32_e32 v25, 0xffff0000, v213
	v_mul_f32_e32 v16, v16, v26
	v_mul_f32_e32 v17, v17, v24
	v_mul_f32_e32 v18, v18, v27
	v_mul_f32_e32 v19, v19, v25
	v_cvt_pk_bf16_f32 v16, v20, v16
	v_cvt_pk_bf16_f32 v17, v21, v17
	v_cvt_pk_bf16_f32 v18, v22, v18
	v_cvt_pk_bf16_f32 v19, v23, v19
	global_store_dwordx4 v[84:85], v[16:19], off offset:16
	s_nop 0
	v_exp_f32_e32 v20, v14
	v_exp_f32_e32 v18, v12
	v_exp_f32_e32 v19, v13
	v_exp_f32_e32 v21, v15
	v_fma_f32 v20, -v20, v20, 1.0
	v_fma_f32 v18, -v18, v18, 1.0
	v_fma_f32 v19, -v19, v19, 1.0
	v_fma_f32 v21, -v21, v21, 1.0
	v_max_f32_e32 v18, 0, v18
	v_max_f32_e32 v19, 0, v19
	v_max_f32_e32 v20, 0, v20
	v_max_f32_e32 v21, 0, v21
	v_sqrt_f32_e32 v18, v18
	v_sqrt_f32_e32 v19, v19
	v_sqrt_f32_e32 v20, v20
	v_sqrt_f32_e32 v21, v21
	v_mul_f32_e32 v8, v8, v18
	v_mul_f32_e32 v9, v9, v19
	v_mul_f32_e32 v10, v10, v20
	v_mul_f32_e32 v11, v11, v21
	s_nop 0
	v_lshlrev_b32_e32 v18, 16, v214
	v_and_b32_e32 v16, 0xffff0000, v214
	v_lshlrev_b32_e32 v19, 16, v215
	v_and_b32_e32 v17, 0xffff0000, v215
	v_mul_f32_e32 v8, v8, v18
	v_mul_f32_e32 v9, v9, v16
	v_mul_f32_e32 v10, v10, v19
	v_mul_f32_e32 v11, v11, v17
	v_cvt_pk_bf16_f32 v8, v12, v8
	v_cvt_pk_bf16_f32 v9, v13, v9
	v_cvt_pk_bf16_f32 v10, v14, v10
	v_cvt_pk_bf16_f32 v11, v15, v11
	global_store_dwordx4 v[76:77], v[8:11], off offset:16
	s_nop 0
	v_exp_f32_e32 v12, v6
	v_exp_f32_e32 v10, v4
	v_exp_f32_e32 v11, v5
	v_exp_f32_e32 v13, v7
	v_fma_f32 v12, -v12, v12, 1.0
	v_fma_f32 v10, -v10, v10, 1.0
	v_fma_f32 v11, -v11, v11, 1.0
	v_fma_f32 v13, -v13, v13, 1.0
	v_max_f32_e32 v10, 0, v10
	v_max_f32_e32 v11, 0, v11
	v_max_f32_e32 v12, 0, v12
	v_max_f32_e32 v13, 0, v13
	v_sqrt_f32_e32 v10, v10
	v_sqrt_f32_e32 v11, v11
	v_sqrt_f32_e32 v12, v12
	v_sqrt_f32_e32 v13, v13
	v_mul_f32_e32 v0, v0, v10
	v_mul_f32_e32 v1, v1, v11
	v_mul_f32_e32 v2, v2, v12
	v_mul_f32_e32 v3, v3, v13
	s_nop 0
	v_lshlrev_b32_e32 v10, 16, v216
	v_and_b32_e32 v8, 0xffff0000, v216
	v_lshlrev_b32_e32 v11, 16, v217
	v_and_b32_e32 v9, 0xffff0000, v217
	v_mul_f32_e32 v0, v0, v10
	v_mul_f32_e32 v1, v1, v8
	v_mul_f32_e32 v2, v2, v11
	v_mul_f32_e32 v3, v3, v9
	v_cvt_pk_bf16_f32 v0, v4, v0
	v_cvt_pk_bf16_f32 v1, v5, v1
	v_cvt_pk_bf16_f32 v2, v6, v2
	v_cvt_pk_bf16_f32 v3, v7, v3
	global_store_dwordx4 v[80:81], v[0:3], off offset:16
	s_cbranch_scc1 .LBB0_693
	s_andn2_b64 vcc, exec, s[12:13]
	s_cbranch_vccnz .LBB0_692
	s_barrier
	s_branch .LBB0_692
